# attention: context K/V of (b,h) staged once per workgroup round in LDS via LDS-DMA (double-buffered, 1 barrier/item); rpb bias as dwordx4; hand-written FNet stage A
# speedup vs baseline: 1.3128x; 1.0287x over previous
.LBB0_364:
	s_and_b64 vcc, exec, s[0:1]
	s_cbranch_vccz .LBB0_368
	s_sub_i32 s0, s13, s10
	s_and_b32 s1, s0, 7
	s_bfe_u32 s2, s0, 0x20003
	s_lshr_b32 s3, s0, 5
	s_lshl_b32 s6, s1, 3
	s_add_i32 s6, s6, s29
	v_and_b32_e32 v128, 63, v143
	v_and_b32_e32 v129, 15, v128
	v_lshrrev_b32_e32 v130, 4, v128
	s_lshl_b32 s7, s3, 12
	s_add_i32 s7, s7, s6
	s_addk_i32 s7, 0x400
	s_mul_i32 s7, s7, 0xe00
	s_lshl_b32 s8, s2, 7
	s_add_i32 s7, s7, s8
	s_add_u32 s7, s7, 0x5e00400
	s_add_u32 s8, s4, s7
	s_addc_u32 s9, s5, 0
	v_mul_u32_u24_e32 v131, 0x38000, v129
	v_lshl_add_u32 v131, v130, 4, v131
	global_load_dwordx4 v[0:3], v131, s[8:9]
	global_load_dwordx4 v[4:7], v131, s[8:9] offset:64
	s_add_u32 s8, s8, 0x380000
	s_addc_u32 s9, s9, 0
	global_load_dwordx4 v[8:11], v131, s[8:9]
	global_load_dwordx4 v[12:15], v131, s[8:9] offset:64
	s_add_u32 s8, s8, 0x380000
	s_addc_u32 s9, s9, 0
	global_load_dwordx4 v[16:19], v131, s[8:9]
	global_load_dwordx4 v[20:23], v131, s[8:9] offset:64
	s_add_u32 s8, s8, 0x380000
	s_addc_u32 s9, s9, 0
	global_load_dwordx4 v[24:27], v131, s[8:9]
	global_load_dwordx4 v[28:31], v131, s[8:9] offset:64
	v_lshlrev_b32_e32 v132, 7, v129
	v_lshl_add_u32 v133, v130, 3, v132
	v_lshl_add_u32 v132, v130, 4, v132
	v_add_u32_e32 v209, 0x1000, v132
	v_add_u32_e32 v210, 0x1000, v133
	global_load_dwordx4 v[32:35], v132, s[42:43] offset:0
	global_load_dwordx4 v[40:43], v132, s[40:41] offset:0
	global_load_dwordx4 v[36:39], v132, s[42:43] offset:64
	global_load_dwordx4 v[44:47], v132, s[40:41] offset:64
	global_load_dwordx4 v[48:51], v132, s[42:43] offset:2048
	global_load_dwordx4 v[56:59], v132, s[40:41] offset:2048
	global_load_dwordx4 v[52:55], v132, s[42:43] offset:2112
	global_load_dwordx4 v[60:63], v132, s[40:41] offset:2112
	s_waitcnt vmcnt(8)
	s_waitcnt vmcnt(4)
	v_mfma_f32_16x16x32_bf16 v[64:67], v[0:3], v[32:35], 0
	v_mfma_f32_16x16x32_bf16 v[68:71], v[8:11], v[32:35], 0
	v_mfma_f32_16x16x32_bf16 v[72:75], v[0:3], v[40:43], 0
	v_mfma_f32_16x16x32_bf16 v[76:79], v[8:11], v[40:43], 0
	v_mfma_f32_16x16x32_bf16 v[64:67], v[4:7], v[36:39], v[64:67]
	v_mfma_f32_16x16x32_bf16 v[68:71], v[12:15], v[36:39], v[68:71]
	v_mfma_f32_16x16x32_bf16 v[72:75], v[4:7], v[44:47], v[72:75]
	v_mfma_f32_16x16x32_bf16 v[76:79], v[12:15], v[44:47], v[76:79]
	s_nop 7
	s_nop 3
	v_cvt_pk_bf16_f32 v80, v64, v65
	v_cvt_pk_bf16_f32 v81, v66, v67
	v_cvt_pk_bf16_f32 v82, v68, v69
	v_cvt_pk_bf16_f32 v83, v70, v71
	v_cvt_pk_bf16_f32 v144, v72, v73
	v_cvt_pk_bf16_f32 v145, v74, v75
	v_cvt_pk_bf16_f32 v146, v76, v77
	v_cvt_pk_bf16_f32 v147, v78, v79
	s_nop 1
	v_mfma_f32_16x16x32_bf16 v[64:67], v[16:19], v[32:35], 0
	v_mfma_f32_16x16x32_bf16 v[68:71], v[24:27], v[32:35], 0
	v_mfma_f32_16x16x32_bf16 v[72:75], v[16:19], v[40:43], 0
	v_mfma_f32_16x16x32_bf16 v[76:79], v[24:27], v[40:43], 0
	v_mfma_f32_16x16x32_bf16 v[64:67], v[20:23], v[36:39], v[64:67]
	v_mfma_f32_16x16x32_bf16 v[68:71], v[28:31], v[36:39], v[68:71]
	v_mfma_f32_16x16x32_bf16 v[72:75], v[20:23], v[44:47], v[72:75]
	v_mfma_f32_16x16x32_bf16 v[76:79], v[28:31], v[44:47], v[76:79]
	global_load_dwordx4 v[32:35], v209, s[42:43] offset:0
	global_load_dwordx4 v[40:43], v209, s[40:41] offset:0
	global_load_dwordx4 v[36:39], v209, s[42:43] offset:64
	global_load_dwordx4 v[44:47], v209, s[40:41] offset:64
	s_nop 3
	v_cvt_pk_bf16_f32 v96, v64, v65
	v_cvt_pk_bf16_f32 v97, v66, v67
	v_cvt_pk_bf16_f32 v98, v68, v69
	v_cvt_pk_bf16_f32 v99, v70, v71
	v_cvt_pk_bf16_f32 v160, v72, v73
	v_cvt_pk_bf16_f32 v161, v74, v75
	v_cvt_pk_bf16_f32 v162, v76, v77
	v_cvt_pk_bf16_f32 v163, v78, v79
	s_nop 1
	s_waitcnt vmcnt(4)
	v_mfma_f32_16x16x32_bf16 v[64:67], v[0:3], v[48:51], 0
	v_mfma_f32_16x16x32_bf16 v[68:71], v[8:11], v[48:51], 0
	v_mfma_f32_16x16x32_bf16 v[72:75], v[0:3], v[56:59], 0
	v_mfma_f32_16x16x32_bf16 v[76:79], v[8:11], v[56:59], 0
	v_mfma_f32_16x16x32_bf16 v[64:67], v[4:7], v[52:55], v[64:67]
	v_mfma_f32_16x16x32_bf16 v[68:71], v[12:15], v[52:55], v[68:71]
	v_mfma_f32_16x16x32_bf16 v[72:75], v[4:7], v[60:63], v[72:75]
	v_mfma_f32_16x16x32_bf16 v[76:79], v[12:15], v[60:63], v[76:79]
	s_nop 7
	s_nop 3
	v_cvt_pk_bf16_f32 v84, v64, v65
	v_cvt_pk_bf16_f32 v85, v66, v67
	v_cvt_pk_bf16_f32 v86, v68, v69
	v_cvt_pk_bf16_f32 v87, v70, v71
	v_cvt_pk_bf16_f32 v148, v72, v73
	v_cvt_pk_bf16_f32 v149, v74, v75
	v_cvt_pk_bf16_f32 v150, v76, v77
	v_cvt_pk_bf16_f32 v151, v78, v79
	s_nop 1
	v_mfma_f32_16x16x32_bf16 v[64:67], v[16:19], v[48:51], 0
	v_mfma_f32_16x16x32_bf16 v[68:71], v[24:27], v[48:51], 0
	v_mfma_f32_16x16x32_bf16 v[72:75], v[16:19], v[56:59], 0
	v_mfma_f32_16x16x32_bf16 v[76:79], v[24:27], v[56:59], 0
	v_mfma_f32_16x16x32_bf16 v[64:67], v[20:23], v[52:55], v[64:67]
	v_mfma_f32_16x16x32_bf16 v[68:71], v[28:31], v[52:55], v[68:71]
	v_mfma_f32_16x16x32_bf16 v[72:75], v[20:23], v[60:63], v[72:75]
	v_mfma_f32_16x16x32_bf16 v[76:79], v[28:31], v[60:63], v[76:79]
	global_load_dwordx4 v[48:51], v209, s[42:43] offset:2048
	global_load_dwordx4 v[56:59], v209, s[40:41] offset:2048
	global_load_dwordx4 v[52:55], v209, s[42:43] offset:2112
	global_load_dwordx4 v[60:63], v209, s[40:41] offset:2112
	s_nop 3
	v_cvt_pk_bf16_f32 v100, v64, v65
	v_cvt_pk_bf16_f32 v101, v66, v67
	v_cvt_pk_bf16_f32 v102, v68, v69
	v_cvt_pk_bf16_f32 v103, v70, v71
	v_cvt_pk_bf16_f32 v164, v72, v73
	v_cvt_pk_bf16_f32 v165, v74, v75
	v_cvt_pk_bf16_f32 v166, v76, v77
	v_cvt_pk_bf16_f32 v167, v78, v79
	s_nop 1
	s_waitcnt vmcnt(4)
	v_mfma_f32_16x16x32_bf16 v[64:67], v[0:3], v[32:35], 0
	v_mfma_f32_16x16x32_bf16 v[68:71], v[8:11], v[32:35], 0
	v_mfma_f32_16x16x32_bf16 v[72:75], v[0:3], v[40:43], 0
	v_mfma_f32_16x16x32_bf16 v[76:79], v[8:11], v[40:43], 0
	v_mfma_f32_16x16x32_bf16 v[64:67], v[4:7], v[36:39], v[64:67]
	v_mfma_f32_16x16x32_bf16 v[68:71], v[12:15], v[36:39], v[68:71]
	v_mfma_f32_16x16x32_bf16 v[72:75], v[4:7], v[44:47], v[72:75]
	v_mfma_f32_16x16x32_bf16 v[76:79], v[12:15], v[44:47], v[76:79]
	s_nop 7
	s_nop 3
	v_cvt_pk_bf16_f32 v88, v64, v65
	v_cvt_pk_bf16_f32 v89, v66, v67
	v_cvt_pk_bf16_f32 v90, v68, v69
	v_cvt_pk_bf16_f32 v91, v70, v71
	v_cvt_pk_bf16_f32 v152, v72, v73
	v_cvt_pk_bf16_f32 v153, v74, v75
	v_cvt_pk_bf16_f32 v154, v76, v77
	v_cvt_pk_bf16_f32 v155, v78, v79
	s_nop 1
	v_mfma_f32_16x16x32_bf16 v[64:67], v[16:19], v[32:35], 0
	v_mfma_f32_16x16x32_bf16 v[68:71], v[24:27], v[32:35], 0
	v_mfma_f32_16x16x32_bf16 v[72:75], v[16:19], v[40:43], 0
	v_mfma_f32_16x16x32_bf16 v[76:79], v[24:27], v[40:43], 0
	v_mfma_f32_16x16x32_bf16 v[64:67], v[20:23], v[36:39], v[64:67]
	v_mfma_f32_16x16x32_bf16 v[68:71], v[28:31], v[36:39], v[68:71]
	v_mfma_f32_16x16x32_bf16 v[72:75], v[20:23], v[44:47], v[72:75]
	v_mfma_f32_16x16x32_bf16 v[76:79], v[28:31], v[44:47], v[76:79]
	global_load_dwordx2 v[112:113], v133, s[42:43] offset:0
	global_load_dwordx2 v[114:115], v133, s[42:43] offset:32
	global_load_dwordx2 v[120:121], v133, s[40:41] offset:0
	global_load_dwordx2 v[122:123], v133, s[40:41] offset:32
	global_load_dwordx2 v[116:117], v133, s[42:43] offset:64
	global_load_dwordx2 v[118:119], v133, s[42:43] offset:96
	global_load_dwordx2 v[124:125], v133, s[40:41] offset:64
	global_load_dwordx2 v[126:127], v133, s[40:41] offset:96
	s_nop 3
	v_cvt_pk_bf16_f32 v104, v64, v65
	v_cvt_pk_bf16_f32 v105, v66, v67
	v_cvt_pk_bf16_f32 v106, v68, v69
	v_cvt_pk_bf16_f32 v107, v70, v71
	v_cvt_pk_bf16_f32 v168, v72, v73
	v_cvt_pk_bf16_f32 v169, v74, v75
	v_cvt_pk_bf16_f32 v170, v76, v77
	v_cvt_pk_bf16_f32 v171, v78, v79
	s_nop 1
	s_waitcnt vmcnt(8)
	v_mfma_f32_16x16x32_bf16 v[64:67], v[0:3], v[48:51], 0
	v_mfma_f32_16x16x32_bf16 v[68:71], v[8:11], v[48:51], 0
	v_mfma_f32_16x16x32_bf16 v[72:75], v[0:3], v[56:59], 0
	v_mfma_f32_16x16x32_bf16 v[76:79], v[8:11], v[56:59], 0
	v_mfma_f32_16x16x32_bf16 v[64:67], v[4:7], v[52:55], v[64:67]
	v_mfma_f32_16x16x32_bf16 v[68:71], v[12:15], v[52:55], v[68:71]
	v_mfma_f32_16x16x32_bf16 v[72:75], v[4:7], v[60:63], v[72:75]
	v_mfma_f32_16x16x32_bf16 v[76:79], v[12:15], v[60:63], v[76:79]
	s_nop 7
	s_nop 3
	v_cvt_pk_bf16_f32 v92, v64, v65
	v_cvt_pk_bf16_f32 v93, v66, v67
	v_cvt_pk_bf16_f32 v94, v68, v69
	v_cvt_pk_bf16_f32 v95, v70, v71
	v_cvt_pk_bf16_f32 v156, v72, v73
	v_cvt_pk_bf16_f32 v157, v74, v75
	v_cvt_pk_bf16_f32 v158, v76, v77
	v_cvt_pk_bf16_f32 v159, v78, v79
	s_nop 1
	v_mfma_f32_16x16x32_bf16 v[64:67], v[16:19], v[48:51], 0
	v_mfma_f32_16x16x32_bf16 v[68:71], v[24:27], v[48:51], 0
	v_mfma_f32_16x16x32_bf16 v[72:75], v[16:19], v[56:59], 0
	v_mfma_f32_16x16x32_bf16 v[76:79], v[24:27], v[56:59], 0
	v_mfma_f32_16x16x32_bf16 v[64:67], v[20:23], v[52:55], v[64:67]
	v_mfma_f32_16x16x32_bf16 v[68:71], v[28:31], v[52:55], v[68:71]
	v_mfma_f32_16x16x32_bf16 v[72:75], v[20:23], v[60:63], v[72:75]
	v_mfma_f32_16x16x32_bf16 v[76:79], v[28:31], v[60:63], v[76:79]
	global_load_dwordx2 v[48:49], v133, s[42:43] offset:2048
	global_load_dwordx2 v[50:51], v133, s[42:43] offset:2080
	global_load_dwordx2 v[56:57], v133, s[40:41] offset:2048
	global_load_dwordx2 v[58:59], v133, s[40:41] offset:2080
	global_load_dwordx2 v[52:53], v133, s[42:43] offset:2112
	global_load_dwordx2 v[54:55], v133, s[42:43] offset:2144
	global_load_dwordx2 v[60:61], v133, s[40:41] offset:2112
	global_load_dwordx2 v[62:63], v133, s[40:41] offset:2144
	s_nop 3
	v_cvt_pk_bf16_f32 v108, v64, v65
	v_cvt_pk_bf16_f32 v109, v66, v67
	v_cvt_pk_bf16_f32 v110, v68, v69
	v_cvt_pk_bf16_f32 v111, v70, v71
	v_cvt_pk_bf16_f32 v172, v72, v73
	v_cvt_pk_bf16_f32 v173, v74, v75
	v_cvt_pk_bf16_f32 v174, v76, v77
	v_cvt_pk_bf16_f32 v175, v78, v79
	s_nop 1
	v_lshlrev_b32_e32 v134, 12, v130
	v_lshl_add_u32 v134, v129, 4, v134
	s_lshl_b32 s7, s29, 1
	v_add_u32_e32 v134, s7, v134
	v_add_u32_e32 v135, 0x10000, v134
	v_lshlrev_b32_e32 v206, 2, v130
	v_mul_u32_u24_e32 v206, s6, v206
	v_mov_b32_e32 v207, 0x39800000
	s_waitcnt vmcnt(8)
	s_mul_i32 s70, s6, 0
	s_mul_i32 s71, s6, 0
	s_add_i32 s71, s71, s70
	v_add_u32_e32 v208, s71, v206
	v_and_b32_e32 v208, 0xfff, v208
	v_cvt_f32_u32_e32 v208, v208
	v_mul_f32_e32 v208, v208, v207
	v_cos_f32_e32 v32, v208
	v_sin_f32_e32 v36, v208
	s_mul_i32 s71, s6, 1
	s_add_i32 s71, s71, s70
	v_add_u32_e32 v208, s71, v206
	v_and_b32_e32 v208, 0xfff, v208
	v_cvt_f32_u32_e32 v208, v208
	v_mul_f32_e32 v208, v208, v207
	v_cos_f32_e32 v33, v208
	v_sin_f32_e32 v37, v208
	s_mul_i32 s71, s6, 2
	s_add_i32 s71, s71, s70
	v_add_u32_e32 v208, s71, v206
	v_and_b32_e32 v208, 0xfff, v208
	v_cvt_f32_u32_e32 v208, v208
	v_mul_f32_e32 v208, v208, v207
	v_cos_f32_e32 v34, v208
	v_sin_f32_e32 v38, v208
	s_mul_i32 s71, s6, 3
	s_add_i32 s71, s71, s70
	v_add_u32_e32 v208, s71, v206
	v_and_b32_e32 v208, 0xfff, v208
	v_cvt_f32_u32_e32 v208, v208
	v_mul_f32_e32 v208, v208, v207
	v_cos_f32_e32 v35, v208
	v_sin_f32_e32 v39, v208
	v_mfma_f32_16x16x32_bf16 v[0:3], v[112:115], v[80:83], 0
	v_mfma_f32_16x16x32_bf16 v[4:7], v[120:123], v[144:147], 0
	v_mfma_f32_16x16x32_bf16 v[8:11], v[112:115], v[144:147], 0
	v_mfma_f32_16x16x32_bf16 v[8:11], v[120:123], v[80:83], v[8:11]
	v_mfma_f32_16x16x32_bf16 v[0:3], v[116:119], v[96:99], v[0:3]
	v_mfma_f32_16x16x32_bf16 v[4:7], v[124:127], v[160:163], v[4:7]
	v_mfma_f32_16x16x32_bf16 v[8:11], v[116:119], v[160:163], v[8:11]
	v_mfma_f32_16x16x32_bf16 v[8:11], v[124:127], v[96:99], v[8:11]
	v_mfma_f32_16x16x32_bf16 v[12:15], v[112:115], v[84:87], 0
	v_mfma_f32_16x16x32_bf16 v[16:19], v[120:123], v[148:151], 0
	v_mfma_f32_16x16x32_bf16 v[20:23], v[112:115], v[148:151], 0
	v_mfma_f32_16x16x32_bf16 v[20:23], v[120:123], v[84:87], v[20:23]
	v_mfma_f32_16x16x32_bf16 v[12:15], v[116:119], v[100:103], v[12:15]
	v_mfma_f32_16x16x32_bf16 v[16:19], v[124:127], v[164:167], v[16:19]
	v_mfma_f32_16x16x32_bf16 v[20:23], v[116:119], v[164:167], v[20:23]
	v_mfma_f32_16x16x32_bf16 v[20:23], v[124:127], v[100:103], v[20:23]
	v_sub_f32_e32 v0, v0, v4
	v_sub_f32_e32 v1, v1, v5
	v_sub_f32_e32 v2, v2, v6
	v_sub_f32_e32 v3, v3, v7
	v_mul_f32_e32 v4, v8, v36
	v_fma_f32 v4, v0, v32, -v4
	v_mul_f32_e32 v8, v8, v32
	v_fma_f32 v8, v0, v36, v8
	v_mul_f32_e32 v5, v9, v37
	v_fma_f32 v5, v1, v33, -v5
	v_mul_f32_e32 v9, v9, v33
	v_fma_f32 v9, v1, v37, v9
	v_mul_f32_e32 v6, v10, v38
	v_fma_f32 v6, v2, v34, -v6
	v_mul_f32_e32 v10, v10, v34
	v_fma_f32 v10, v2, v38, v10
	v_mul_f32_e32 v7, v11, v39
	v_fma_f32 v7, v3, v35, -v7
	v_mul_f32_e32 v11, v11, v35
	v_fma_f32 v11, v3, v39, v11
	v_cvt_pk_bf16_f32 v0, v4, v8
	v_cvt_pk_bf16_f32 v1, v5, v9
	v_cvt_pk_bf16_f32 v2, v6, v10
	v_cvt_pk_bf16_f32 v3, v7, v11
	ds_write_b16 v134, v0 offset:0
	v_lshrrev_b32_e32 v4, 16, v0
	ds_write_b16 v135, v4 offset:0
	ds_write_b16 v134, v1 offset:1024
	v_lshrrev_b32_e32 v5, 16, v1
	ds_write_b16 v135, v5 offset:1024
	ds_write_b16 v134, v2 offset:2048
	v_lshrrev_b32_e32 v6, 16, v2
	ds_write_b16 v135, v6 offset:2048
	ds_write_b16 v134, v3 offset:3072
	v_lshrrev_b32_e32 v7, 16, v3
	ds_write_b16 v135, v7 offset:3072
	v_mfma_f32_16x16x32_bf16 v[0:3], v[112:115], v[88:91], 0
	v_mfma_f32_16x16x32_bf16 v[4:7], v[120:123], v[152:155], 0
	v_mfma_f32_16x16x32_bf16 v[8:11], v[112:115], v[152:155], 0
	v_mfma_f32_16x16x32_bf16 v[8:11], v[120:123], v[88:91], v[8:11]
	v_mfma_f32_16x16x32_bf16 v[0:3], v[116:119], v[104:107], v[0:3]
	v_mfma_f32_16x16x32_bf16 v[4:7], v[124:127], v[168:171], v[4:7]
	v_mfma_f32_16x16x32_bf16 v[8:11], v[116:119], v[168:171], v[8:11]
	v_mfma_f32_16x16x32_bf16 v[8:11], v[124:127], v[104:107], v[8:11]
	v_sub_f32_e32 v12, v12, v16
	v_sub_f32_e32 v13, v13, v17
	v_sub_f32_e32 v14, v14, v18
	v_sub_f32_e32 v15, v15, v19
	v_mul_f32_e32 v16, v20, v36
	v_fma_f32 v16, v12, v32, -v16
	v_mul_f32_e32 v20, v20, v32
	v_fma_f32 v20, v12, v36, v20
	v_mul_f32_e32 v17, v21, v37
	v_fma_f32 v17, v13, v33, -v17
	v_mul_f32_e32 v21, v21, v33
	v_fma_f32 v21, v13, v37, v21
	v_mul_f32_e32 v18, v22, v38
	v_fma_f32 v18, v14, v34, -v18
	v_mul_f32_e32 v22, v22, v34
	v_fma_f32 v22, v14, v38, v22
	v_mul_f32_e32 v19, v23, v39
	v_fma_f32 v19, v15, v35, -v19
	v_mul_f32_e32 v23, v23, v35
	v_fma_f32 v23, v15, v39, v23
	v_cvt_pk_bf16_f32 v12, v16, v20
	v_cvt_pk_bf16_f32 v13, v17, v21
	v_cvt_pk_bf16_f32 v14, v18, v22
	v_cvt_pk_bf16_f32 v15, v19, v23
	ds_write_b16 v134, v12 offset:256
	v_lshrrev_b32_e32 v16, 16, v12
	ds_write_b16 v135, v16 offset:256
	ds_write_b16 v134, v13 offset:1280
	v_lshrrev_b32_e32 v17, 16, v13
	ds_write_b16 v135, v17 offset:1280
	ds_write_b16 v134, v14 offset:2304
	v_lshrrev_b32_e32 v18, 16, v14
	ds_write_b16 v135, v18 offset:2304
	ds_write_b16 v134, v15 offset:3328
	v_lshrrev_b32_e32 v19, 16, v15
	ds_write_b16 v135, v19 offset:3328
	v_mfma_f32_16x16x32_bf16 v[12:15], v[112:115], v[92:95], 0
	v_mfma_f32_16x16x32_bf16 v[16:19], v[120:123], v[156:159], 0
	v_mfma_f32_16x16x32_bf16 v[20:23], v[112:115], v[156:159], 0
	v_mfma_f32_16x16x32_bf16 v[20:23], v[120:123], v[92:95], v[20:23]
	v_mfma_f32_16x16x32_bf16 v[12:15], v[116:119], v[108:111], v[12:15]
	v_mfma_f32_16x16x32_bf16 v[16:19], v[124:127], v[172:175], v[16:19]
	v_mfma_f32_16x16x32_bf16 v[20:23], v[116:119], v[172:175], v[20:23]
	v_mfma_f32_16x16x32_bf16 v[20:23], v[124:127], v[108:111], v[20:23]
	global_load_dwordx2 v[112:113], v210, s[42:43] offset:0
	global_load_dwordx2 v[114:115], v210, s[42:43] offset:32
	global_load_dwordx2 v[120:121], v210, s[40:41] offset:0
	global_load_dwordx2 v[122:123], v210, s[40:41] offset:32
	global_load_dwordx2 v[116:117], v210, s[42:43] offset:64
	global_load_dwordx2 v[118:119], v210, s[42:43] offset:96
	global_load_dwordx2 v[124:125], v210, s[40:41] offset:64
	global_load_dwordx2 v[126:127], v210, s[40:41] offset:96
	v_sub_f32_e32 v0, v0, v4
	v_sub_f32_e32 v1, v1, v5
	v_sub_f32_e32 v2, v2, v6
	v_sub_f32_e32 v3, v3, v7
	v_mul_f32_e32 v4, v8, v36
	v_fma_f32 v4, v0, v32, -v4
	v_mul_f32_e32 v8, v8, v32
	v_fma_f32 v8, v0, v36, v8
	v_mul_f32_e32 v5, v9, v37
	v_fma_f32 v5, v1, v33, -v5
	v_mul_f32_e32 v9, v9, v33
	v_fma_f32 v9, v1, v37, v9
	v_mul_f32_e32 v6, v10, v38
	v_fma_f32 v6, v2, v34, -v6
	v_mul_f32_e32 v10, v10, v34
	v_fma_f32 v10, v2, v38, v10
	v_mul_f32_e32 v7, v11, v39
	v_fma_f32 v7, v3, v35, -v7
	v_mul_f32_e32 v11, v11, v35
	v_fma_f32 v11, v3, v39, v11
	v_cvt_pk_bf16_f32 v0, v4, v8
	v_cvt_pk_bf16_f32 v1, v5, v9
	v_cvt_pk_bf16_f32 v2, v6, v10
	v_cvt_pk_bf16_f32 v3, v7, v11
	ds_write_b16 v134, v0 offset:512
	v_lshrrev_b32_e32 v4, 16, v0
	ds_write_b16 v135, v4 offset:512
	ds_write_b16 v134, v1 offset:1536
	v_lshrrev_b32_e32 v5, 16, v1
	ds_write_b16 v135, v5 offset:1536
	ds_write_b16 v134, v2 offset:2560
	v_lshrrev_b32_e32 v6, 16, v2
	ds_write_b16 v135, v6 offset:2560
	ds_write_b16 v134, v3 offset:3584
	v_lshrrev_b32_e32 v7, 16, v3
	ds_write_b16 v135, v7 offset:3584
	s_waitcnt vmcnt(8)
	s_mul_i32 s70, s6, 16
	s_mul_i32 s71, s6, 0
	s_add_i32 s71, s71, s70
	v_add_u32_e32 v208, s71, v206
	v_and_b32_e32 v208, 0xfff, v208
	v_cvt_f32_u32_e32 v208, v208
	v_mul_f32_e32 v208, v208, v207
	v_cos_f32_e32 v40, v208
	v_sin_f32_e32 v44, v208
	s_mul_i32 s71, s6, 1
	s_add_i32 s71, s71, s70
	v_add_u32_e32 v208, s71, v206
	v_and_b32_e32 v208, 0xfff, v208
	v_cvt_f32_u32_e32 v208, v208
	v_mul_f32_e32 v208, v208, v207
	v_cos_f32_e32 v41, v208
	v_sin_f32_e32 v45, v208
	s_mul_i32 s71, s6, 2
	s_add_i32 s71, s71, s70
	v_add_u32_e32 v208, s71, v206
	v_and_b32_e32 v208, 0xfff, v208
	v_cvt_f32_u32_e32 v208, v208
	v_mul_f32_e32 v208, v208, v207
	v_cos_f32_e32 v42, v208
	v_sin_f32_e32 v46, v208
	s_mul_i32 s71, s6, 3
	s_add_i32 s71, s71, s70
	v_add_u32_e32 v208, s71, v206
	v_and_b32_e32 v208, 0xfff, v208
	v_cvt_f32_u32_e32 v208, v208
	v_mul_f32_e32 v208, v208, v207
	v_cos_f32_e32 v43, v208
	v_sin_f32_e32 v47, v208
	v_mfma_f32_16x16x32_bf16 v[0:3], v[48:51], v[80:83], 0
	v_mfma_f32_16x16x32_bf16 v[4:7], v[56:59], v[144:147], 0
	v_mfma_f32_16x16x32_bf16 v[8:11], v[48:51], v[144:147], 0
	v_mfma_f32_16x16x32_bf16 v[8:11], v[56:59], v[80:83], v[8:11]
	v_mfma_f32_16x16x32_bf16 v[0:3], v[52:55], v[96:99], v[0:3]
	v_mfma_f32_16x16x32_bf16 v[4:7], v[60:63], v[160:163], v[4:7]
	v_mfma_f32_16x16x32_bf16 v[8:11], v[52:55], v[160:163], v[8:11]
	v_mfma_f32_16x16x32_bf16 v[8:11], v[60:63], v[96:99], v[8:11]
	v_sub_f32_e32 v12, v12, v16
	v_sub_f32_e32 v13, v13, v17
	v_sub_f32_e32 v14, v14, v18
	v_sub_f32_e32 v15, v15, v19
	v_mul_f32_e32 v16, v20, v36
	v_fma_f32 v16, v12, v32, -v16
	v_mul_f32_e32 v20, v20, v32
	v_fma_f32 v20, v12, v36, v20
	v_mul_f32_e32 v17, v21, v37
	v_fma_f32 v17, v13, v33, -v17
	v_mul_f32_e32 v21, v21, v33
	v_fma_f32 v21, v13, v37, v21
	v_mul_f32_e32 v18, v22, v38
	v_fma_f32 v18, v14, v34, -v18
	v_mul_f32_e32 v22, v22, v34
	v_fma_f32 v22, v14, v38, v22
	v_mul_f32_e32 v19, v23, v39
	v_fma_f32 v19, v15, v35, -v19
	v_mul_f32_e32 v23, v23, v35
	v_fma_f32 v23, v15, v39, v23
	v_cvt_pk_bf16_f32 v12, v16, v20
	v_cvt_pk_bf16_f32 v13, v17, v21
	v_cvt_pk_bf16_f32 v14, v18, v22
	v_cvt_pk_bf16_f32 v15, v19, v23
	ds_write_b16 v134, v12 offset:768
	v_lshrrev_b32_e32 v16, 16, v12
	ds_write_b16 v135, v16 offset:768
	ds_write_b16 v134, v13 offset:1792
	v_lshrrev_b32_e32 v17, 16, v13
	ds_write_b16 v135, v17 offset:1792
	ds_write_b16 v134, v14 offset:2816
	v_lshrrev_b32_e32 v18, 16, v14
	ds_write_b16 v135, v18 offset:2816
	ds_write_b16 v134, v15 offset:3840
	v_lshrrev_b32_e32 v19, 16, v15
	ds_write_b16 v135, v19 offset:3840
	v_mfma_f32_16x16x32_bf16 v[12:15], v[48:51], v[84:87], 0
	v_mfma_f32_16x16x32_bf16 v[16:19], v[56:59], v[148:151], 0
	v_mfma_f32_16x16x32_bf16 v[20:23], v[48:51], v[148:151], 0
	v_mfma_f32_16x16x32_bf16 v[20:23], v[56:59], v[84:87], v[20:23]
	v_mfma_f32_16x16x32_bf16 v[12:15], v[52:55], v[100:103], v[12:15]
	v_mfma_f32_16x16x32_bf16 v[16:19], v[60:63], v[164:167], v[16:19]
	v_mfma_f32_16x16x32_bf16 v[20:23], v[52:55], v[164:167], v[20:23]
	v_mfma_f32_16x16x32_bf16 v[20:23], v[60:63], v[100:103], v[20:23]
	v_sub_f32_e32 v0, v0, v4
	v_sub_f32_e32 v1, v1, v5
	v_sub_f32_e32 v2, v2, v6
	v_sub_f32_e32 v3, v3, v7
	v_mul_f32_e32 v4, v8, v44
	v_fma_f32 v4, v0, v40, -v4
	v_mul_f32_e32 v8, v8, v40
	v_fma_f32 v8, v0, v44, v8
	v_mul_f32_e32 v5, v9, v45
	v_fma_f32 v5, v1, v41, -v5
	v_mul_f32_e32 v9, v9, v41
	v_fma_f32 v9, v1, v45, v9
	v_mul_f32_e32 v6, v10, v46
	v_fma_f32 v6, v2, v42, -v6
	v_mul_f32_e32 v10, v10, v42
	v_fma_f32 v10, v2, v46, v10
	v_mul_f32_e32 v7, v11, v47
	v_fma_f32 v7, v3, v43, -v7
	v_mul_f32_e32 v11, v11, v43
	v_fma_f32 v11, v3, v47, v11
	v_cvt_pk_bf16_f32 v0, v4, v8
	v_cvt_pk_bf16_f32 v1, v5, v9
	v_cvt_pk_bf16_f32 v2, v6, v10
	v_cvt_pk_bf16_f32 v3, v7, v11
	ds_write_b16 v134, v0 offset:16384
	v_lshrrev_b32_e32 v4, 16, v0
	ds_write_b16 v135, v4 offset:16384
	ds_write_b16 v134, v1 offset:17408
	v_lshrrev_b32_e32 v5, 16, v1
	ds_write_b16 v135, v5 offset:17408
	ds_write_b16 v134, v2 offset:18432
	v_lshrrev_b32_e32 v6, 16, v2
	ds_write_b16 v135, v6 offset:18432
	ds_write_b16 v134, v3 offset:19456
	v_lshrrev_b32_e32 v7, 16, v3
	ds_write_b16 v135, v7 offset:19456
	v_mfma_f32_16x16x32_bf16 v[0:3], v[48:51], v[88:91], 0
	v_mfma_f32_16x16x32_bf16 v[4:7], v[56:59], v[152:155], 0
	v_mfma_f32_16x16x32_bf16 v[8:11], v[48:51], v[152:155], 0
	v_mfma_f32_16x16x32_bf16 v[8:11], v[56:59], v[88:91], v[8:11]
	v_mfma_f32_16x16x32_bf16 v[0:3], v[52:55], v[104:107], v[0:3]
	v_mfma_f32_16x16x32_bf16 v[4:7], v[60:63], v[168:171], v[4:7]
	v_mfma_f32_16x16x32_bf16 v[8:11], v[52:55], v[168:171], v[8:11]
	v_mfma_f32_16x16x32_bf16 v[8:11], v[60:63], v[104:107], v[8:11]
	v_sub_f32_e32 v12, v12, v16
	v_sub_f32_e32 v13, v13, v17
	v_sub_f32_e32 v14, v14, v18
	v_sub_f32_e32 v15, v15, v19
	v_mul_f32_e32 v16, v20, v44
	v_fma_f32 v16, v12, v40, -v16
	v_mul_f32_e32 v20, v20, v40
	v_fma_f32 v20, v12, v44, v20
	v_mul_f32_e32 v17, v21, v45
	v_fma_f32 v17, v13, v41, -v17
	v_mul_f32_e32 v21, v21, v41
	v_fma_f32 v21, v13, v45, v21
	v_mul_f32_e32 v18, v22, v46
	v_fma_f32 v18, v14, v42, -v18
	v_mul_f32_e32 v22, v22, v42
	v_fma_f32 v22, v14, v46, v22
	v_mul_f32_e32 v19, v23, v47
	v_fma_f32 v19, v15, v43, -v19
	v_mul_f32_e32 v23, v23, v43
	v_fma_f32 v23, v15, v47, v23
	v_cvt_pk_bf16_f32 v12, v16, v20
	v_cvt_pk_bf16_f32 v13, v17, v21
	v_cvt_pk_bf16_f32 v14, v18, v22
	v_cvt_pk_bf16_f32 v15, v19, v23
	ds_write_b16 v134, v12 offset:16640
	v_lshrrev_b32_e32 v16, 16, v12
	ds_write_b16 v135, v16 offset:16640
	ds_write_b16 v134, v13 offset:17664
	v_lshrrev_b32_e32 v17, 16, v13
	ds_write_b16 v135, v17 offset:17664
	ds_write_b16 v134, v14 offset:18688
	v_lshrrev_b32_e32 v18, 16, v14
	ds_write_b16 v135, v18 offset:18688
	ds_write_b16 v134, v15 offset:19712
	v_lshrrev_b32_e32 v19, 16, v15
	ds_write_b16 v135, v19 offset:19712
	v_mfma_f32_16x16x32_bf16 v[12:15], v[48:51], v[92:95], 0
	v_mfma_f32_16x16x32_bf16 v[16:19], v[56:59], v[156:159], 0
	v_mfma_f32_16x16x32_bf16 v[20:23], v[48:51], v[156:159], 0
	v_mfma_f32_16x16x32_bf16 v[20:23], v[56:59], v[92:95], v[20:23]
	v_mfma_f32_16x16x32_bf16 v[12:15], v[52:55], v[108:111], v[12:15]
	v_mfma_f32_16x16x32_bf16 v[16:19], v[60:63], v[172:175], v[16:19]
	v_mfma_f32_16x16x32_bf16 v[20:23], v[52:55], v[172:175], v[20:23]
	v_mfma_f32_16x16x32_bf16 v[20:23], v[60:63], v[108:111], v[20:23]
	global_load_dwordx2 v[48:49], v210, s[42:43] offset:2048
	global_load_dwordx2 v[50:51], v210, s[42:43] offset:2080
	global_load_dwordx2 v[56:57], v210, s[40:41] offset:2048
	global_load_dwordx2 v[58:59], v210, s[40:41] offset:2080
	global_load_dwordx2 v[52:53], v210, s[42:43] offset:2112
	global_load_dwordx2 v[54:55], v210, s[42:43] offset:2144
	global_load_dwordx2 v[60:61], v210, s[40:41] offset:2112
	global_load_dwordx2 v[62:63], v210, s[40:41] offset:2144
	v_sub_f32_e32 v0, v0, v4
	v_sub_f32_e32 v1, v1, v5
	v_sub_f32_e32 v2, v2, v6
	v_sub_f32_e32 v3, v3, v7
	v_mul_f32_e32 v4, v8, v44
	v_fma_f32 v4, v0, v40, -v4
	v_mul_f32_e32 v8, v8, v40
	v_fma_f32 v8, v0, v44, v8
	v_mul_f32_e32 v5, v9, v45
	v_fma_f32 v5, v1, v41, -v5
	v_mul_f32_e32 v9, v9, v41
	v_fma_f32 v9, v1, v45, v9
	v_mul_f32_e32 v6, v10, v46
	v_fma_f32 v6, v2, v42, -v6
	v_mul_f32_e32 v10, v10, v42
	v_fma_f32 v10, v2, v46, v10
	v_mul_f32_e32 v7, v11, v47
	v_fma_f32 v7, v3, v43, -v7
	v_mul_f32_e32 v11, v11, v43
	v_fma_f32 v11, v3, v47, v11
	v_cvt_pk_bf16_f32 v0, v4, v8
	v_cvt_pk_bf16_f32 v1, v5, v9
	v_cvt_pk_bf16_f32 v2, v6, v10
	v_cvt_pk_bf16_f32 v3, v7, v11
	ds_write_b16 v134, v0 offset:16896
	v_lshrrev_b32_e32 v4, 16, v0
	ds_write_b16 v135, v4 offset:16896
	ds_write_b16 v134, v1 offset:17920
	v_lshrrev_b32_e32 v5, 16, v1
	ds_write_b16 v135, v5 offset:17920
	ds_write_b16 v134, v2 offset:18944
	v_lshrrev_b32_e32 v6, 16, v2
	ds_write_b16 v135, v6 offset:18944
	ds_write_b16 v134, v3 offset:19968
	v_lshrrev_b32_e32 v7, 16, v3
	ds_write_b16 v135, v7 offset:19968
	s_waitcnt vmcnt(8)
	s_mul_i32 s70, s6, 32
	s_mul_i32 s71, s6, 0
	s_add_i32 s71, s71, s70
	v_add_u32_e32 v208, s71, v206
	v_and_b32_e32 v208, 0xfff, v208
	v_cvt_f32_u32_e32 v208, v208
	v_mul_f32_e32 v208, v208, v207
	v_cos_f32_e32 v32, v208
	v_sin_f32_e32 v36, v208
	s_mul_i32 s71, s6, 1
	s_add_i32 s71, s71, s70
	v_add_u32_e32 v208, s71, v206
	v_and_b32_e32 v208, 0xfff, v208
	v_cvt_f32_u32_e32 v208, v208
	v_mul_f32_e32 v208, v208, v207
	v_cos_f32_e32 v33, v208
	v_sin_f32_e32 v37, v208
	s_mul_i32 s71, s6, 2
	s_add_i32 s71, s71, s70
	v_add_u32_e32 v208, s71, v206
	v_and_b32_e32 v208, 0xfff, v208
	v_cvt_f32_u32_e32 v208, v208
	v_mul_f32_e32 v208, v208, v207
	v_cos_f32_e32 v34, v208
	v_sin_f32_e32 v38, v208
	s_mul_i32 s71, s6, 3
	s_add_i32 s71, s71, s70
	v_add_u32_e32 v208, s71, v206
	v_and_b32_e32 v208, 0xfff, v208
	v_cvt_f32_u32_e32 v208, v208
	v_mul_f32_e32 v208, v208, v207
	v_cos_f32_e32 v35, v208
	v_sin_f32_e32 v39, v208
	v_mfma_f32_16x16x32_bf16 v[0:3], v[112:115], v[80:83], 0
	v_mfma_f32_16x16x32_bf16 v[4:7], v[120:123], v[144:147], 0
	v_mfma_f32_16x16x32_bf16 v[8:11], v[112:115], v[144:147], 0
	v_mfma_f32_16x16x32_bf16 v[8:11], v[120:123], v[80:83], v[8:11]
	v_mfma_f32_16x16x32_bf16 v[0:3], v[116:119], v[96:99], v[0:3]
	v_mfma_f32_16x16x32_bf16 v[4:7], v[124:127], v[160:163], v[4:7]
	v_mfma_f32_16x16x32_bf16 v[8:11], v[116:119], v[160:163], v[8:11]
	v_mfma_f32_16x16x32_bf16 v[8:11], v[124:127], v[96:99], v[8:11]
	v_sub_f32_e32 v12, v12, v16
	v_sub_f32_e32 v13, v13, v17
	v_sub_f32_e32 v14, v14, v18
	v_sub_f32_e32 v15, v15, v19
	v_mul_f32_e32 v16, v20, v44
	v_fma_f32 v16, v12, v40, -v16
	v_mul_f32_e32 v20, v20, v40
	v_fma_f32 v20, v12, v44, v20
	v_mul_f32_e32 v17, v21, v45
	v_fma_f32 v17, v13, v41, -v17
	v_mul_f32_e32 v21, v21, v41
	v_fma_f32 v21, v13, v45, v21
	v_mul_f32_e32 v18, v22, v46
	v_fma_f32 v18, v14, v42, -v18
	v_mul_f32_e32 v22, v22, v42
	v_fma_f32 v22, v14, v46, v22
	v_mul_f32_e32 v19, v23, v47
	v_fma_f32 v19, v15, v43, -v19
	v_mul_f32_e32 v23, v23, v43
	v_fma_f32 v23, v15, v47, v23
	v_cvt_pk_bf16_f32 v12, v16, v20
	v_cvt_pk_bf16_f32 v13, v17, v21
	v_cvt_pk_bf16_f32 v14, v18, v22
	v_cvt_pk_bf16_f32 v15, v19, v23
	ds_write_b16 v134, v12 offset:17152
	v_lshrrev_b32_e32 v16, 16, v12
	ds_write_b16 v135, v16 offset:17152
	ds_write_b16 v134, v13 offset:18176
	v_lshrrev_b32_e32 v17, 16, v13
	ds_write_b16 v135, v17 offset:18176
	ds_write_b16 v134, v14 offset:19200
	v_lshrrev_b32_e32 v18, 16, v14
	ds_write_b16 v135, v18 offset:19200
	ds_write_b16 v134, v15 offset:20224
	v_lshrrev_b32_e32 v19, 16, v15
	ds_write_b16 v135, v19 offset:20224
	v_mfma_f32_16x16x32_bf16 v[12:15], v[112:115], v[84:87], 0
	v_mfma_f32_16x16x32_bf16 v[16:19], v[120:123], v[148:151], 0
	v_mfma_f32_16x16x32_bf16 v[20:23], v[112:115], v[148:151], 0
	v_mfma_f32_16x16x32_bf16 v[20:23], v[120:123], v[84:87], v[20:23]
	v_mfma_f32_16x16x32_bf16 v[12:15], v[116:119], v[100:103], v[12:15]
	v_mfma_f32_16x16x32_bf16 v[16:19], v[124:127], v[164:167], v[16:19]
	v_mfma_f32_16x16x32_bf16 v[20:23], v[116:119], v[164:167], v[20:23]
	v_mfma_f32_16x16x32_bf16 v[20:23], v[124:127], v[100:103], v[20:23]
	v_sub_f32_e32 v0, v0, v4
	v_sub_f32_e32 v1, v1, v5
	v_sub_f32_e32 v2, v2, v6
	v_sub_f32_e32 v3, v3, v7
	v_mul_f32_e32 v4, v8, v36
	v_fma_f32 v4, v0, v32, -v4
	v_mul_f32_e32 v8, v8, v32
	v_fma_f32 v8, v0, v36, v8
	v_mul_f32_e32 v5, v9, v37
	v_fma_f32 v5, v1, v33, -v5
	v_mul_f32_e32 v9, v9, v33
	v_fma_f32 v9, v1, v37, v9
	v_mul_f32_e32 v6, v10, v38
	v_fma_f32 v6, v2, v34, -v6
	v_mul_f32_e32 v10, v10, v34
	v_fma_f32 v10, v2, v38, v10
	v_mul_f32_e32 v7, v11, v39
	v_fma_f32 v7, v3, v35, -v7
	v_mul_f32_e32 v11, v11, v35
	v_fma_f32 v11, v3, v39, v11
	v_cvt_pk_bf16_f32 v0, v4, v8
	v_cvt_pk_bf16_f32 v1, v5, v9
	v_cvt_pk_bf16_f32 v2, v6, v10
	v_cvt_pk_bf16_f32 v3, v7, v11
	ds_write_b16 v134, v0 offset:32768
	v_lshrrev_b32_e32 v4, 16, v0
	ds_write_b16 v135, v4 offset:32768
	ds_write_b16 v134, v1 offset:33792
	v_lshrrev_b32_e32 v5, 16, v1
	ds_write_b16 v135, v5 offset:33792
	ds_write_b16 v134, v2 offset:34816
	v_lshrrev_b32_e32 v6, 16, v2
	ds_write_b16 v135, v6 offset:34816
	ds_write_b16 v134, v3 offset:35840
	v_lshrrev_b32_e32 v7, 16, v3
	ds_write_b16 v135, v7 offset:35840
	v_mfma_f32_16x16x32_bf16 v[0:3], v[112:115], v[88:91], 0
	v_mfma_f32_16x16x32_bf16 v[4:7], v[120:123], v[152:155], 0
	v_mfma_f32_16x16x32_bf16 v[8:11], v[112:115], v[152:155], 0
	v_mfma_f32_16x16x32_bf16 v[8:11], v[120:123], v[88:91], v[8:11]
	v_mfma_f32_16x16x32_bf16 v[0:3], v[116:119], v[104:107], v[0:3]
	v_mfma_f32_16x16x32_bf16 v[4:7], v[124:127], v[168:171], v[4:7]
	v_mfma_f32_16x16x32_bf16 v[8:11], v[116:119], v[168:171], v[8:11]
	v_mfma_f32_16x16x32_bf16 v[8:11], v[124:127], v[104:107], v[8:11]
	v_sub_f32_e32 v12, v12, v16
	v_sub_f32_e32 v13, v13, v17
	v_sub_f32_e32 v14, v14, v18
	v_sub_f32_e32 v15, v15, v19
	v_mul_f32_e32 v16, v20, v36
	v_fma_f32 v16, v12, v32, -v16
	v_mul_f32_e32 v20, v20, v32
	v_fma_f32 v20, v12, v36, v20
	v_mul_f32_e32 v17, v21, v37
	v_fma_f32 v17, v13, v33, -v17
	v_mul_f32_e32 v21, v21, v33
	v_fma_f32 v21, v13, v37, v21
	v_mul_f32_e32 v18, v22, v38
	v_fma_f32 v18, v14, v34, -v18
	v_mul_f32_e32 v22, v22, v34
	v_fma_f32 v22, v14, v38, v22
	v_mul_f32_e32 v19, v23, v39
	v_fma_f32 v19, v15, v35, -v19
	v_mul_f32_e32 v23, v23, v35
	v_fma_f32 v23, v15, v39, v23
	v_cvt_pk_bf16_f32 v12, v16, v20
	v_cvt_pk_bf16_f32 v13, v17, v21
	v_cvt_pk_bf16_f32 v14, v18, v22
	v_cvt_pk_bf16_f32 v15, v19, v23
	ds_write_b16 v134, v12 offset:33024
	v_lshrrev_b32_e32 v16, 16, v12
	ds_write_b16 v135, v16 offset:33024
	ds_write_b16 v134, v13 offset:34048
	v_lshrrev_b32_e32 v17, 16, v13
	ds_write_b16 v135, v17 offset:34048
	ds_write_b16 v134, v14 offset:35072
	v_lshrrev_b32_e32 v18, 16, v14
	ds_write_b16 v135, v18 offset:35072
	ds_write_b16 v134, v15 offset:36096
	v_lshrrev_b32_e32 v19, 16, v15
	ds_write_b16 v135, v19 offset:36096
	v_mfma_f32_16x16x32_bf16 v[12:15], v[112:115], v[92:95], 0
	v_mfma_f32_16x16x32_bf16 v[16:19], v[120:123], v[156:159], 0
	v_mfma_f32_16x16x32_bf16 v[20:23], v[112:115], v[156:159], 0
	v_mfma_f32_16x16x32_bf16 v[20:23], v[120:123], v[92:95], v[20:23]
	v_mfma_f32_16x16x32_bf16 v[12:15], v[116:119], v[108:111], v[12:15]
	v_mfma_f32_16x16x32_bf16 v[16:19], v[124:127], v[172:175], v[16:19]
	v_mfma_f32_16x16x32_bf16 v[20:23], v[116:119], v[172:175], v[20:23]
	v_mfma_f32_16x16x32_bf16 v[20:23], v[124:127], v[108:111], v[20:23]
	v_sub_f32_e32 v0, v0, v4
	v_sub_f32_e32 v1, v1, v5
	v_sub_f32_e32 v2, v2, v6
	v_sub_f32_e32 v3, v3, v7
	v_mul_f32_e32 v4, v8, v36
	v_fma_f32 v4, v0, v32, -v4
	v_mul_f32_e32 v8, v8, v32
	v_fma_f32 v8, v0, v36, v8
	v_mul_f32_e32 v5, v9, v37
	v_fma_f32 v5, v1, v33, -v5
	v_mul_f32_e32 v9, v9, v33
	v_fma_f32 v9, v1, v37, v9
	v_mul_f32_e32 v6, v10, v38
	v_fma_f32 v6, v2, v34, -v6
	v_mul_f32_e32 v10, v10, v34
	v_fma_f32 v10, v2, v38, v10
	v_mul_f32_e32 v7, v11, v39
	v_fma_f32 v7, v3, v35, -v7
	v_mul_f32_e32 v11, v11, v35
	v_fma_f32 v11, v3, v39, v11
	v_cvt_pk_bf16_f32 v0, v4, v8
	v_cvt_pk_bf16_f32 v1, v5, v9
	v_cvt_pk_bf16_f32 v2, v6, v10
	v_cvt_pk_bf16_f32 v3, v7, v11
	ds_write_b16 v134, v0 offset:33280
	v_lshrrev_b32_e32 v4, 16, v0
	ds_write_b16 v135, v4 offset:33280
	ds_write_b16 v134, v1 offset:34304
	v_lshrrev_b32_e32 v5, 16, v1
	ds_write_b16 v135, v5 offset:34304
	ds_write_b16 v134, v2 offset:35328
	v_lshrrev_b32_e32 v6, 16, v2
	ds_write_b16 v135, v6 offset:35328
	ds_write_b16 v134, v3 offset:36352
	v_lshrrev_b32_e32 v7, 16, v3
	ds_write_b16 v135, v7 offset:36352
	s_waitcnt vmcnt(0)
	s_mul_i32 s70, s6, 48
	s_mul_i32 s71, s6, 0
	s_add_i32 s71, s71, s70
	v_add_u32_e32 v208, s71, v206
	v_and_b32_e32 v208, 0xfff, v208
	v_cvt_f32_u32_e32 v208, v208
	v_mul_f32_e32 v208, v208, v207
	v_cos_f32_e32 v40, v208
	v_sin_f32_e32 v44, v208
	s_mul_i32 s71, s6, 1
	s_add_i32 s71, s71, s70
	v_add_u32_e32 v208, s71, v206
	v_and_b32_e32 v208, 0xfff, v208
	v_cvt_f32_u32_e32 v208, v208
	v_mul_f32_e32 v208, v208, v207
	v_cos_f32_e32 v41, v208
	v_sin_f32_e32 v45, v208
	s_mul_i32 s71, s6, 2
	s_add_i32 s71, s71, s70
	v_add_u32_e32 v208, s71, v206
	v_and_b32_e32 v208, 0xfff, v208
	v_cvt_f32_u32_e32 v208, v208
	v_mul_f32_e32 v208, v208, v207
	v_cos_f32_e32 v42, v208
	v_sin_f32_e32 v46, v208
	s_mul_i32 s71, s6, 3
	s_add_i32 s71, s71, s70
	v_add_u32_e32 v208, s71, v206
	v_and_b32_e32 v208, 0xfff, v208
	v_cvt_f32_u32_e32 v208, v208
	v_mul_f32_e32 v208, v208, v207
	v_cos_f32_e32 v43, v208
	v_sin_f32_e32 v47, v208
	v_mfma_f32_16x16x32_bf16 v[0:3], v[48:51], v[80:83], 0
	v_mfma_f32_16x16x32_bf16 v[4:7], v[56:59], v[144:147], 0
	v_mfma_f32_16x16x32_bf16 v[8:11], v[48:51], v[144:147], 0
	v_mfma_f32_16x16x32_bf16 v[8:11], v[56:59], v[80:83], v[8:11]
	v_mfma_f32_16x16x32_bf16 v[0:3], v[52:55], v[96:99], v[0:3]
	v_mfma_f32_16x16x32_bf16 v[4:7], v[60:63], v[160:163], v[4:7]
	v_mfma_f32_16x16x32_bf16 v[8:11], v[52:55], v[160:163], v[8:11]
	v_mfma_f32_16x16x32_bf16 v[8:11], v[60:63], v[96:99], v[8:11]
	v_sub_f32_e32 v12, v12, v16
	v_sub_f32_e32 v13, v13, v17
	v_sub_f32_e32 v14, v14, v18
	v_sub_f32_e32 v15, v15, v19
	v_mul_f32_e32 v16, v20, v36
	v_fma_f32 v16, v12, v32, -v16
	v_mul_f32_e32 v20, v20, v32
	v_fma_f32 v20, v12, v36, v20
	v_mul_f32_e32 v17, v21, v37
	v_fma_f32 v17, v13, v33, -v17
	v_mul_f32_e32 v21, v21, v33
	v_fma_f32 v21, v13, v37, v21
	v_mul_f32_e32 v18, v22, v38
	v_fma_f32 v18, v14, v34, -v18
	v_mul_f32_e32 v22, v22, v34
	v_fma_f32 v22, v14, v38, v22
	v_mul_f32_e32 v19, v23, v39
	v_fma_f32 v19, v15, v35, -v19
	v_mul_f32_e32 v23, v23, v35
	v_fma_f32 v23, v15, v39, v23
	v_cvt_pk_bf16_f32 v12, v16, v20
	v_cvt_pk_bf16_f32 v13, v17, v21
	v_cvt_pk_bf16_f32 v14, v18, v22
	v_cvt_pk_bf16_f32 v15, v19, v23
	ds_write_b16 v134, v12 offset:33536
	v_lshrrev_b32_e32 v16, 16, v12
	ds_write_b16 v135, v16 offset:33536
	ds_write_b16 v134, v13 offset:34560
	v_lshrrev_b32_e32 v17, 16, v13
	ds_write_b16 v135, v17 offset:34560
	ds_write_b16 v134, v14 offset:35584
	v_lshrrev_b32_e32 v18, 16, v14
	ds_write_b16 v135, v18 offset:35584
	ds_write_b16 v134, v15 offset:36608
	v_lshrrev_b32_e32 v19, 16, v15
	ds_write_b16 v135, v19 offset:36608
	v_mfma_f32_16x16x32_bf16 v[12:15], v[48:51], v[84:87], 0
	v_mfma_f32_16x16x32_bf16 v[16:19], v[56:59], v[148:151], 0
	v_mfma_f32_16x16x32_bf16 v[20:23], v[48:51], v[148:151], 0
	v_mfma_f32_16x16x32_bf16 v[20:23], v[56:59], v[84:87], v[20:23]
	v_mfma_f32_16x16x32_bf16 v[12:15], v[52:55], v[100:103], v[12:15]
	v_mfma_f32_16x16x32_bf16 v[16:19], v[60:63], v[164:167], v[16:19]
	v_mfma_f32_16x16x32_bf16 v[20:23], v[52:55], v[164:167], v[20:23]
	v_mfma_f32_16x16x32_bf16 v[20:23], v[60:63], v[100:103], v[20:23]
	v_sub_f32_e32 v0, v0, v4
	v_sub_f32_e32 v1, v1, v5
	v_sub_f32_e32 v2, v2, v6
	v_sub_f32_e32 v3, v3, v7
	v_mul_f32_e32 v4, v8, v44
	v_fma_f32 v4, v0, v40, -v4
	v_mul_f32_e32 v8, v8, v40
	v_fma_f32 v8, v0, v44, v8
	v_mul_f32_e32 v5, v9, v45
	v_fma_f32 v5, v1, v41, -v5
	v_mul_f32_e32 v9, v9, v41
	v_fma_f32 v9, v1, v45, v9
	v_mul_f32_e32 v6, v10, v46
	v_fma_f32 v6, v2, v42, -v6
	v_mul_f32_e32 v10, v10, v42
	v_fma_f32 v10, v2, v46, v10
	v_mul_f32_e32 v7, v11, v47
	v_fma_f32 v7, v3, v43, -v7
	v_mul_f32_e32 v11, v11, v43
	v_fma_f32 v11, v3, v47, v11
	v_cvt_pk_bf16_f32 v0, v4, v8
	v_cvt_pk_bf16_f32 v1, v5, v9
	v_cvt_pk_bf16_f32 v2, v6, v10
	v_cvt_pk_bf16_f32 v3, v7, v11
	ds_write_b16 v134, v0 offset:49152
	v_lshrrev_b32_e32 v4, 16, v0
	ds_write_b16 v135, v4 offset:49152
	ds_write_b16 v134, v1 offset:50176
	v_lshrrev_b32_e32 v5, 16, v1
	ds_write_b16 v135, v5 offset:50176
	ds_write_b16 v134, v2 offset:51200
	v_lshrrev_b32_e32 v6, 16, v2
	ds_write_b16 v135, v6 offset:51200
	ds_write_b16 v134, v3 offset:52224
	v_lshrrev_b32_e32 v7, 16, v3
	ds_write_b16 v135, v7 offset:52224
	v_mfma_f32_16x16x32_bf16 v[0:3], v[48:51], v[88:91], 0
	v_mfma_f32_16x16x32_bf16 v[4:7], v[56:59], v[152:155], 0
	v_mfma_f32_16x16x32_bf16 v[8:11], v[48:51], v[152:155], 0
	v_mfma_f32_16x16x32_bf16 v[8:11], v[56:59], v[88:91], v[8:11]
	v_mfma_f32_16x16x32_bf16 v[0:3], v[52:55], v[104:107], v[0:3]
	v_mfma_f32_16x16x32_bf16 v[4:7], v[60:63], v[168:171], v[4:7]
	v_mfma_f32_16x16x32_bf16 v[8:11], v[52:55], v[168:171], v[8:11]
	v_mfma_f32_16x16x32_bf16 v[8:11], v[60:63], v[104:107], v[8:11]
	v_sub_f32_e32 v12, v12, v16
	v_sub_f32_e32 v13, v13, v17
	v_sub_f32_e32 v14, v14, v18
	v_sub_f32_e32 v15, v15, v19
	v_mul_f32_e32 v16, v20, v44
	v_fma_f32 v16, v12, v40, -v16
	v_mul_f32_e32 v20, v20, v40
	v_fma_f32 v20, v12, v44, v20
	v_mul_f32_e32 v17, v21, v45
	v_fma_f32 v17, v13, v41, -v17
	v_mul_f32_e32 v21, v21, v41
	v_fma_f32 v21, v13, v45, v21
	v_mul_f32_e32 v18, v22, v46
	v_fma_f32 v18, v14, v42, -v18
	v_mul_f32_e32 v22, v22, v42
	v_fma_f32 v22, v14, v46, v22
	v_mul_f32_e32 v19, v23, v47
	v_fma_f32 v19, v15, v43, -v19
	v_mul_f32_e32 v23, v23, v43
	v_fma_f32 v23, v15, v47, v23
	v_cvt_pk_bf16_f32 v12, v16, v20
	v_cvt_pk_bf16_f32 v13, v17, v21
	v_cvt_pk_bf16_f32 v14, v18, v22
	v_cvt_pk_bf16_f32 v15, v19, v23
	ds_write_b16 v134, v12 offset:49408
	v_lshrrev_b32_e32 v16, 16, v12
	ds_write_b16 v135, v16 offset:49408
	ds_write_b16 v134, v13 offset:50432
	v_lshrrev_b32_e32 v17, 16, v13
	ds_write_b16 v135, v17 offset:50432
	ds_write_b16 v134, v14 offset:51456
	v_lshrrev_b32_e32 v18, 16, v14
	ds_write_b16 v135, v18 offset:51456
	ds_write_b16 v134, v15 offset:52480
	v_lshrrev_b32_e32 v19, 16, v15
	ds_write_b16 v135, v19 offset:52480
	v_mfma_f32_16x16x32_bf16 v[12:15], v[48:51], v[92:95], 0
	v_mfma_f32_16x16x32_bf16 v[16:19], v[56:59], v[156:159], 0
	v_mfma_f32_16x16x32_bf16 v[20:23], v[48:51], v[156:159], 0
	v_mfma_f32_16x16x32_bf16 v[20:23], v[56:59], v[92:95], v[20:23]
	v_mfma_f32_16x16x32_bf16 v[12:15], v[52:55], v[108:111], v[12:15]
	v_mfma_f32_16x16x32_bf16 v[16:19], v[60:63], v[172:175], v[16:19]
	v_mfma_f32_16x16x32_bf16 v[20:23], v[52:55], v[172:175], v[20:23]
	v_mfma_f32_16x16x32_bf16 v[20:23], v[60:63], v[108:111], v[20:23]
	v_sub_f32_e32 v0, v0, v4
	v_sub_f32_e32 v1, v1, v5
	v_sub_f32_e32 v2, v2, v6
	v_sub_f32_e32 v3, v3, v7
	v_mul_f32_e32 v4, v8, v44
	v_fma_f32 v4, v0, v40, -v4
	v_mul_f32_e32 v8, v8, v40
	v_fma_f32 v8, v0, v44, v8
	v_mul_f32_e32 v5, v9, v45
	v_fma_f32 v5, v1, v41, -v5
	v_mul_f32_e32 v9, v9, v41
	v_fma_f32 v9, v1, v45, v9
	v_mul_f32_e32 v6, v10, v46
	v_fma_f32 v6, v2, v42, -v6
	v_mul_f32_e32 v10, v10, v42
	v_fma_f32 v10, v2, v46, v10
	v_mul_f32_e32 v7, v11, v47
	v_fma_f32 v7, v3, v43, -v7
	v_mul_f32_e32 v11, v11, v43
	v_fma_f32 v11, v3, v47, v11
	v_cvt_pk_bf16_f32 v0, v4, v8
	v_cvt_pk_bf16_f32 v1, v5, v9
	v_cvt_pk_bf16_f32 v2, v6, v10
	v_cvt_pk_bf16_f32 v3, v7, v11
	ds_write_b16 v134, v0 offset:49664
	v_lshrrev_b32_e32 v4, 16, v0
	ds_write_b16 v135, v4 offset:49664
	ds_write_b16 v134, v1 offset:50688
	v_lshrrev_b32_e32 v5, 16, v1
	ds_write_b16 v135, v5 offset:50688
	ds_write_b16 v134, v2 offset:51712
	v_lshrrev_b32_e32 v6, 16, v2
	ds_write_b16 v135, v6 offset:51712
	ds_write_b16 v134, v3 offset:52736
	v_lshrrev_b32_e32 v7, 16, v3
	ds_write_b16 v135, v7 offset:52736
	s_nop 7
	s_nop 1
	v_sub_f32_e32 v12, v12, v16
	v_sub_f32_e32 v13, v13, v17
	v_sub_f32_e32 v14, v14, v18
	v_sub_f32_e32 v15, v15, v19
	v_mul_f32_e32 v16, v20, v44
	v_fma_f32 v16, v12, v40, -v16
	v_mul_f32_e32 v20, v20, v40
	v_fma_f32 v20, v12, v44, v20
	v_mul_f32_e32 v17, v21, v45
	v_fma_f32 v17, v13, v41, -v17
	v_mul_f32_e32 v21, v21, v41
	v_fma_f32 v21, v13, v45, v21
	v_mul_f32_e32 v18, v22, v46
	v_fma_f32 v18, v14, v42, -v18
	v_mul_f32_e32 v22, v22, v42
	v_fma_f32 v22, v14, v46, v22
	v_mul_f32_e32 v19, v23, v47
	v_fma_f32 v19, v15, v43, -v19
	v_mul_f32_e32 v23, v23, v43
	v_fma_f32 v23, v15, v47, v23
	v_cvt_pk_bf16_f32 v12, v16, v20
	v_cvt_pk_bf16_f32 v13, v17, v21
	v_cvt_pk_bf16_f32 v14, v18, v22
	v_cvt_pk_bf16_f32 v15, v19, v23
	ds_write_b16 v134, v12 offset:49920
	v_lshrrev_b32_e32 v16, 16, v12
	ds_write_b16 v135, v16 offset:49920
	ds_write_b16 v134, v13 offset:50944
	v_lshrrev_b32_e32 v17, 16, v13
	ds_write_b16 v135, v17 offset:50944
	ds_write_b16 v134, v14 offset:51968
	v_lshrrev_b32_e32 v18, 16, v14
	ds_write_b16 v135, v18 offset:51968
	ds_write_b16 v134, v15 offset:52992
	v_lshrrev_b32_e32 v19, 16, v15
	ds_write_b16 v135, v19 offset:52992
	s_waitcnt lgkmcnt(0)
	s_barrier
	v_lshlrev_b32_e32 v64, 4, v143
	v_lshrrev_b32_e32 v65, 6, v143
	v_lshlrev_b32_e32 v65, 14, v65
	v_lshl_add_u32 v65, v128, 7, v65
	s_lshl_b32 s7, s3, 2
	s_add_i32 s7, s7, s2
	s_lshl_b32 s7, s7, 20
	s_lshl_b32 s8, s1, 4
	s_add_i32 s7, s7, s8
	s_add_u32 s8, s44, s7
	s_addc_u32 s9, s45, 0
	ds_read_b128 v[66:69], v64 offset:0
	ds_read_b128 v[70:73], v64 offset:8192
	ds_read_b128 v[74:77], v64 offset:16384
	ds_read_b128 v[78:81], v64 offset:24576
	ds_read_b128 v[82:85], v64 offset:32768
	ds_read_b128 v[86:89], v64 offset:40960
	ds_read_b128 v[90:93], v64 offset:49152
	ds_read_b128 v[94:97], v64 offset:57344
	s_waitcnt lgkmcnt(0)
	s_add_u32 s70, s8, 0x0
	s_addc_u32 s71, s9, 0
	global_store_dwordx4 v65, v[66:69], s[70:71]
	s_add_u32 s70, s8, 0x20000
	s_addc_u32 s71, s9, 0
	global_store_dwordx4 v65, v[70:73], s[70:71]
	s_add_u32 s70, s8, 0x40000
	s_addc_u32 s71, s9, 0
	global_store_dwordx4 v65, v[74:77], s[70:71]
	s_add_u32 s70, s8, 0x60000
	s_addc_u32 s71, s9, 0
	global_store_dwordx4 v65, v[78:81], s[70:71]
	s_add_u32 s70, s8, 0x80000
	s_addc_u32 s71, s9, 0
	global_store_dwordx4 v65, v[82:85], s[70:71]
	s_add_u32 s70, s8, 0xa0000
	s_addc_u32 s71, s9, 0
	global_store_dwordx4 v65, v[86:89], s[70:71]
	s_add_u32 s70, s8, 0xc0000
	s_addc_u32 s71, s9, 0
	global_store_dwordx4 v65, v[90:93], s[70:71]
	s_add_u32 s70, s8, 0xe0000
	s_addc_u32 s71, s9, 0
	global_store_dwordx4 v65, v[94:97], s[70:71]
	s_nop 1
	v_add_u32_e32 v64, 0x10000, v64
	ds_read_b128 v[66:69], v64 offset:0
	ds_read_b128 v[70:73], v64 offset:8192
	ds_read_b128 v[74:77], v64 offset:16384
	ds_read_b128 v[78:81], v64 offset:24576
	ds_read_b128 v[82:85], v64 offset:32768
	ds_read_b128 v[86:89], v64 offset:40960
	ds_read_b128 v[90:93], v64 offset:49152
	ds_read_b128 v[94:97], v64 offset:57344
	s_waitcnt lgkmcnt(0)
	s_add_u32 s70, s8, 0x2000
	s_addc_u32 s71, s9, 0
	global_store_dwordx4 v65, v[66:69], s[70:71]
	s_add_u32 s70, s8, 0x22000
	s_addc_u32 s71, s9, 0
	global_store_dwordx4 v65, v[70:73], s[70:71]
	s_add_u32 s70, s8, 0x42000
	s_addc_u32 s71, s9, 0
	global_store_dwordx4 v65, v[74:77], s[70:71]
	s_add_u32 s70, s8, 0x62000
	s_addc_u32 s71, s9, 0
	global_store_dwordx4 v65, v[78:81], s[70:71]
	s_add_u32 s70, s8, 0x82000
	s_addc_u32 s71, s9, 0
	global_store_dwordx4 v65, v[82:85], s[70:71]
	s_add_u32 s70, s8, 0xa2000
	s_addc_u32 s71, s9, 0
	global_store_dwordx4 v65, v[86:89], s[70:71]
	s_add_u32 s70, s8, 0xc2000
	s_addc_u32 s71, s9, 0
	global_store_dwordx4 v65, v[90:93], s[70:71]
	s_add_u32 s70, s8, 0xe2000
	s_addc_u32 s71, s9, 0
	global_store_dwordx4 v65, v[94:97], s[70:71]
	s_barrier

.Lss3_done:
.LBB0_436:
	s_and_b32 s0, s94, 0x4c0
	s_cmp_eq_u32 s0, 0
	s_cbranch_scc1 .LBB0_612
	s_barrier
	s_bitcmp1_b32 s94, 6
	s_cselect_b64 s[0:1], -1, 0
	s_and_b32 s8, s94, 0x400
	s_and_b64 vcc, exec, s[0:1]
	s_mov_b64 s[6:7], s[0:1]
	s_cbranch_vccnz .LBB0_439
	s_cmp_lg_u32 s8, 0
	v_readlane_b32 s9, v245, 37
	s_cselect_b64 s[6:7], -1, 0
	s_add_i32 s9, s9, -12
	s_cmp_lt_u32 s9, 11
	s_cselect_b64 s[10:11], -1, 0
	s_and_b64 s[6:7], s[6:7], s[10:11]

.LBB0_479:
	s_andn2_b64 vcc, exec, s[0:1]
	s_cbranch_vccnz .LBB0_609
	s_sub_i32 s86, s12, s13
	s_and_b32 s0, s86, 3
	s_bfe_u32 s1, s86, 0x10002
	s_bfe_u32 s6, s86, 0x20003
	s_bfe_u32 s7, s86, 0x50005
	s_lshr_b32 s8, s86, 10
	s_lshl_b32 s7, s7, 1
	s_or_b32 s1, s1, s7
	s_sub_i32 s7, s1, 4
	s_max_i32 s7, s7, 0
	s_min_i32 s7, s7, 56
	s_lshl_b32 s9, s0, 4
	s_sub_i32 s9, s9, 8
	s_max_i32 s9, s9, 0
	s_min_i32 s9, s9, 32
	v_and_b32_e32 v206, 15, v205
	v_lshrrev_b32_e32 v207, 4, v205
	s_mul_i32 s10, s6, 15
	s_add_i32 s10, s10, s7
	s_sub_i32 s10, s10, s1
	s_add_i32 s10, s10, 7
	s_mul_i32 s10, s10, 31
	s_add_i32 s10, s10, s9
	s_lshl_b32 s11, s0, 4
	s_sub_i32 s10, s10, s11
	s_add_i32 s10, s10, 15
	v_lshlrev_b32_e32 v214, 3, v207
	v_sub_u32_e32 v214, v214, v206
	v_add_u32_e32 v214, s10, v214
	v_ashrrev_i32_e32 v215, 31, v214
	v_lshl_add_u64 v[212:213], v[214:215], 2, s[56:57]
	global_load_dwordx4 v[0:3], v[212:213], off offset:0
	global_load_dwordx4 v[4:7], v[212:213], off offset:16
	global_load_dwordx4 v[8:11], v[212:213], off offset:124
	global_load_dwordx4 v[12:15], v[212:213], off offset:140
	global_load_dwordx4 v[16:19], v[212:213], off offset:248
	global_load_dwordx4 v[20:23], v[212:213], off offset:264
	global_load_dwordx4 v[24:27], v[212:213], off offset:372
	global_load_dwordx4 v[28:31], v[212:213], off offset:388
	s_lshl_b32 s10, s8, 12
	s_lshl_b32 s11, s1, 6
	s_add_i32 s10, s10, s11
	s_lshl_b32 s11, s0, 4
	s_add_i32 s10, s10, s11
	s_addk_i32 s10, 0x400
	s_mul_i32 s11, s10, 0xe00
	s_lshl_b32 s16, s6, 7
	s_add_u32 s16, s16, 0x5e00000
	s_add_u32 s18, s4, s16
	s_addc_u32 s19, s5, 0
	s_add_u32 s20, s18, s11
	s_addc_u32 s21, s19, 0
	v_mul_u32_u24_e32 v208, 0xe00, v206
	v_lshl_add_u32 v208, v207, 4, v208
	global_load_dwordx4 v[128:131], v208, s[20:21] offset:1536
	global_load_dwordx4 v[132:135], v208, s[20:21] offset:1600
	v_lshrrev_b32_e32 v209, 2, v206
	v_and_b32_e32 v210, 3, v206
	v_lshl_add_u32 v209, v209, 3, v210
	v_mul_u32_u24_e32 v209, 0xe00, v209
	v_lshl_add_u32 v209, v207, 4, v209
	s_lshl_b32 s10, s8, 12
	s_lshl_b32 s11, s7, 6
	s_add_i32 s10, s10, s11
	s_add_i32 s10, s10, s9
	s_addk_i32 s10, 0x400
	s_mul_i32 s10, s10, 0xe00
	s_add_u32 s22, s18, s10
	s_addc_u32 s23, s19, 0
	s_lshl_b32 s10, s8, 8
	s_mul_i32 s10, s10, 0xe00
	s_add_u32 s24, s18, s10
	s_addc_u32 s25, s19, 0
	s_bfe_u32 s38, s86, 0x1000b
	s_lshl_b32 s38, s38, 16
	v_lshrrev_b32_e32 v214, 6, v186
	v_lshlrev_b32_e32 v211, 4, v205
	v_add_u32_e32 v211, s38, v211
	v_readfirstlane_b32 s11, v214
	s_lshl_b32 s10, s8, 8
	s_lshl_b32 s26, s6, 6
	s_add_i32 s10, s10, s26
	s_lshl_b32 s10, s10, 9
	s_add_u32 s10, s10, 0xa200000
	s_add_u32 s26, s4, s10
	s_addc_u32 s27, s5, 0
	v_mov_b32_e32 v136, v209
	s_add_i32 s10, s11, 0
	s_lshr_b32 s36, s10, 2
	s_lshl_b32 s36, s36, 5
	s_bfe_u32 s37, s10, 0x10001
	s_lshl_b32 s37, s37, 2
	s_add_i32 s36, s36, s37
	s_mul_i32 s36, s36, 0xe00
	s_and_b32 s37, s10, 1
	s_lshl_b32 s37, s37, 6
	s_add_i32 s36, s36, s37
	s_addk_i32 s36, 0x800
	s_add_u32 s36, s24, s36
	s_addc_u32 s37, s25, 0
	v_lshl_add_u64 v[214:215], s[36:37], 0, v[136:137]
	s_lshl_b32 s10, s10, 10
	s_add_i32 m0, s10, s38
	s_nop 0
	global_load_lds_dwordx4 v[214:215], off
	s_add_i32 s10, s11, 8
	s_lshr_b32 s36, s10, 2
	s_lshl_b32 s36, s36, 5
	s_bfe_u32 s37, s10, 0x10001
	s_lshl_b32 s37, s37, 2
	s_add_i32 s36, s36, s37
	s_mul_i32 s36, s36, 0xe00
	s_and_b32 s37, s10, 1
	s_lshl_b32 s37, s37, 6
	s_add_i32 s36, s36, s37
	s_addk_i32 s36, 0x800
	s_add_u32 s36, s24, s36
	s_addc_u32 s37, s25, 0
	v_lshl_add_u64 v[214:215], s[36:37], 0, v[136:137]
	s_lshl_b32 s10, s10, 10
	s_add_i32 m0, s10, s38
	s_nop 0
	global_load_lds_dwordx4 v[214:215], off
	s_add_i32 s10, s11, 16
	s_lshr_b32 s36, s10, 2
	s_lshl_b32 s36, s36, 5
	s_bfe_u32 s37, s10, 0x10001
	s_lshl_b32 s37, s37, 2
	s_add_i32 s36, s36, s37
	s_mul_i32 s36, s36, 0xe00
	s_and_b32 s37, s10, 1
	s_lshl_b32 s37, s37, 6
	s_add_i32 s36, s36, s37
	s_addk_i32 s36, 0x800
	s_add_u32 s36, s24, s36
	s_addc_u32 s37, s25, 0
	v_lshl_add_u64 v[214:215], s[36:37], 0, v[136:137]
	s_lshl_b32 s10, s10, 10
	s_add_i32 m0, s10, s38
	s_nop 0
	global_load_lds_dwordx4 v[214:215], off
	s_add_i32 s10, s11, 24
	s_lshr_b32 s36, s10, 2
	s_lshl_b32 s36, s36, 5
	s_bfe_u32 s37, s10, 0x10001
	s_lshl_b32 s37, s37, 2
	s_add_i32 s36, s36, s37
	s_mul_i32 s36, s36, 0xe00
	s_and_b32 s37, s10, 1
	s_lshl_b32 s37, s37, 6
	s_add_i32 s36, s36, s37
	s_addk_i32 s36, 0x800
	s_add_u32 s36, s24, s36
	s_addc_u32 s37, s25, 0
	v_lshl_add_u64 v[214:215], s[36:37], 0, v[136:137]
	s_lshl_b32 s10, s10, 10
	s_add_i32 m0, s10, s38
	s_nop 0
	global_load_lds_dwordx4 v[214:215], off
	v_lshlrev_b32_e32 v136, 9, v206
	v_lshl_add_u32 v136, v207, 4, v136
	s_add_i32 s10, s11, 0
	s_and_b32 s36, s10, 3
	s_lshl_b32 s36, s36, 13
	s_lshr_b32 s37, s10, 2
	s_lshl_b32 s37, s37, 6
	s_add_i32 s36, s36, s37
	s_add_u32 s36, s26, s36
	s_addc_u32 s37, s27, 0
	v_lshl_add_u64 v[214:215], s[36:37], 0, v[136:137]
	s_lshl_b32 s10, s10, 10
	s_add_i32 s10, s10, s38
	s_add_i32 m0, s10, 0x8000
	s_nop 0
	global_load_lds_dwordx4 v[214:215], off
	s_add_i32 s10, s11, 8
	s_and_b32 s36, s10, 3
	s_lshl_b32 s36, s36, 13
	s_lshr_b32 s37, s10, 2
	s_lshl_b32 s37, s37, 6
	s_add_i32 s36, s36, s37
	s_add_u32 s36, s26, s36
	s_addc_u32 s37, s27, 0
	v_lshl_add_u64 v[214:215], s[36:37], 0, v[136:137]
	s_lshl_b32 s10, s10, 10
	s_add_i32 s10, s10, s38
	s_add_i32 m0, s10, 0x8000
	s_nop 0
	global_load_lds_dwordx4 v[214:215], off
	s_add_i32 s10, s11, 16
	s_and_b32 s36, s10, 3
	s_lshl_b32 s36, s36, 13
	s_lshr_b32 s37, s10, 2
	s_lshl_b32 s37, s37, 6
	s_add_i32 s36, s36, s37
	s_add_u32 s36, s26, s36
	s_addc_u32 s37, s27, 0
	v_lshl_add_u64 v[214:215], s[36:37], 0, v[136:137]
	s_lshl_b32 s10, s10, 10
	s_add_i32 s10, s10, s38
	s_add_i32 m0, s10, 0x8000
	s_nop 0
	global_load_lds_dwordx4 v[214:215], off
	s_add_i32 s10, s11, 24
	s_and_b32 s36, s10, 3
	s_lshl_b32 s36, s36, 13
	s_lshr_b32 s37, s10, 2
	s_lshl_b32 s37, s37, 6
	s_add_i32 s36, s36, s37
	s_add_u32 s36, s26, s36
	s_addc_u32 s37, s27, 0
	v_lshl_add_u64 v[214:215], s[36:37], 0, v[136:137]
	s_lshl_b32 s10, s10, 10
	s_add_i32 s10, s10, s38
	s_add_i32 m0, s10, 0x8000
	s_nop 0
	global_load_lds_dwordx4 v[214:215], off
	global_load_dwordx4 v[138:141], v209, s[22:23] offset:2048
	global_load_dwordx4 v[142:145], v209, s[22:23] offset:2112
	s_add_u32 s22, s22, 0x3800
	s_addc_u32 s23, s23, 0
	global_load_dwordx4 v[146:149], v209, s[22:23] offset:2048
	global_load_dwordx4 v[150:153], v209, s[22:23] offset:2112
	s_add_u32 s22, s22, 0x34800
	s_addc_u32 s23, s23, 0
	global_load_dwordx4 v[154:157], v209, s[22:23] offset:2048
	global_load_dwordx4 v[158:161], v209, s[22:23] offset:2112
	s_add_u32 s22, s22, 0x3800
	s_addc_u32 s23, s23, 0
	global_load_dwordx4 v[162:165], v209, s[22:23] offset:2048
	global_load_dwordx4 v[166:169], v209, s[22:23] offset:2112
	s_add_u32 s22, s22, 0x34800
	s_addc_u32 s23, s23, 0
	global_load_dwordx4 v[170:173], v209, s[22:23] offset:2048
	global_load_dwordx4 v[174:177], v209, s[22:23] offset:2112
	s_add_u32 s22, s22, 0x3800
	s_addc_u32 s23, s23, 0
	global_load_dwordx4 v[178:181], v209, s[22:23] offset:2048
	global_load_dwordx4 v[182:185], v209, s[22:23] offset:2112
	s_add_u32 s22, s22, 0x34800
	s_addc_u32 s23, s23, 0
	s_lshl_b32 s10, s0, 4
	s_sub_i32 s10, s10, 8
	v_add_u32_e32 v210, s10, v206
	v_med3_i32 v210, v210, 0, 48
	v_lshl_add_u32 v214, v207, 3, s9
	v_sub_u32_e32 v210, v214, v210
	v_writelane_b32 v136, s0, 0
	v_writelane_b32 v136, s1, 1
	v_writelane_b32 v136, s6, 2
	v_writelane_b32 v136, s7, 3
	v_writelane_b32 v136, s8, 4
	v_writelane_b32 v136, s9, 5
	v_add_u32_e32 v214, 0, v210
	v_cmp_gt_u32_e64 s[26:27], 16, v214
	v_add_u32_e32 v214, 1, v210
	v_cmp_gt_u32_e64 s[36:37], 16, v214
	v_add_u32_e32 v214, 2, v210
	v_cmp_gt_u32_e64 s[10:11], 16, v214
	v_add_u32_e32 v214, 3, v210
	v_cmp_gt_u32_e64 s[0:1], 16, v214
	v_add_u32_e32 v214, 4, v210
	v_cmp_gt_u32_e64 s[6:7], 16, v214
	v_add_u32_e32 v214, 5, v210
	v_cmp_gt_u32_e64 s[8:9], 16, v214
	v_add_u32_e32 v214, 6, v210
	v_cmp_gt_u32_e64 s[16:17], 16, v214
	v_add_u32_e32 v214, 7, v210
	v_cmp_gt_u32_e64 s[20:21], 16, v214
	v_mov_b32_e32 v216, 0xf2c9f2ca
	s_waitcnt vmcnt(22)
	v_mul_f32_e32 v0, 0x41000000, v0
	v_mul_f32_e32 v1, 0x41000000, v1
	v_mul_f32_e32 v2, 0x41000000, v2
	v_mul_f32_e32 v3, 0x41000000, v3
	v_mul_f32_e32 v4, 0x41000000, v4
	v_mul_f32_e32 v5, 0x41000000, v5
	v_mul_f32_e32 v6, 0x41000000, v6
	v_mul_f32_e32 v7, 0x41000000, v7
	v_cndmask_b32_e64 v0, v216, v0, s[26:27]
	v_cndmask_b32_e64 v1, v216, v1, s[36:37]
	v_cndmask_b32_e64 v2, v216, v2, s[10:11]
	v_cndmask_b32_e64 v3, v216, v3, s[0:1]
	v_cndmask_b32_e64 v4, v216, v4, s[6:7]
	v_cndmask_b32_e64 v5, v216, v5, s[8:9]
	v_cndmask_b32_e64 v6, v216, v6, s[16:17]
	v_cndmask_b32_e64 v7, v216, v7, s[20:21]
	v_mul_f32_e32 v8, 0x41000000, v8
	v_mul_f32_e32 v9, 0x41000000, v9
	v_mul_f32_e32 v10, 0x41000000, v10
	v_mul_f32_e32 v11, 0x41000000, v11
	v_mul_f32_e32 v12, 0x41000000, v12
	v_mul_f32_e32 v13, 0x41000000, v13
	v_mul_f32_e32 v14, 0x41000000, v14
	v_mul_f32_e32 v15, 0x41000000, v15
	v_cndmask_b32_e64 v8, v216, v8, s[26:27]
	v_cndmask_b32_e64 v9, v216, v9, s[36:37]
	v_cndmask_b32_e64 v10, v216, v10, s[10:11]
	v_cndmask_b32_e64 v11, v216, v11, s[0:1]
	v_cndmask_b32_e64 v12, v216, v12, s[6:7]
	v_cndmask_b32_e64 v13, v216, v13, s[8:9]
	v_cndmask_b32_e64 v14, v216, v14, s[16:17]
	v_cndmask_b32_e64 v15, v216, v15, s[20:21]
	v_mul_f32_e32 v16, 0x41000000, v16
	v_mul_f32_e32 v17, 0x41000000, v17
	v_mul_f32_e32 v18, 0x41000000, v18
	v_mul_f32_e32 v19, 0x41000000, v19
	v_mul_f32_e32 v20, 0x41000000, v20
	v_mul_f32_e32 v21, 0x41000000, v21
	v_mul_f32_e32 v22, 0x41000000, v22
	v_mul_f32_e32 v23, 0x41000000, v23
	v_cndmask_b32_e64 v16, v216, v16, s[26:27]
	v_cndmask_b32_e64 v17, v216, v17, s[36:37]
	v_cndmask_b32_e64 v18, v216, v18, s[10:11]
	v_cndmask_b32_e64 v19, v216, v19, s[0:1]
	v_cndmask_b32_e64 v20, v216, v20, s[6:7]
	v_cndmask_b32_e64 v21, v216, v21, s[8:9]
	v_cndmask_b32_e64 v22, v216, v22, s[16:17]
	v_cndmask_b32_e64 v23, v216, v23, s[20:21]
	v_mul_f32_e32 v24, 0x41000000, v24
	v_mul_f32_e32 v25, 0x41000000, v25
	v_mul_f32_e32 v26, 0x41000000, v26
	v_mul_f32_e32 v27, 0x41000000, v27
	v_mul_f32_e32 v28, 0x41000000, v28
	v_mul_f32_e32 v29, 0x41000000, v29
	v_mul_f32_e32 v30, 0x41000000, v30
	v_mul_f32_e32 v31, 0x41000000, v31
	v_cndmask_b32_e64 v24, v216, v24, s[26:27]
	v_cndmask_b32_e64 v25, v216, v25, s[36:37]
	v_cndmask_b32_e64 v26, v216, v26, s[10:11]
	v_cndmask_b32_e64 v27, v216, v27, s[0:1]
	v_cndmask_b32_e64 v28, v216, v28, s[6:7]
	v_cndmask_b32_e64 v29, v216, v29, s[8:9]
	v_cndmask_b32_e64 v30, v216, v30, s[16:17]
	v_cndmask_b32_e64 v31, v216, v31, s[20:21]
	global_load_dwordx4 v[32:35], v[212:213], off offset:496
	global_load_dwordx4 v[36:39], v[212:213], off offset:512
	global_load_dwordx4 v[40:43], v[212:213], off offset:620
	global_load_dwordx4 v[44:47], v[212:213], off offset:636
	global_load_dwordx4 v[48:51], v[212:213], off offset:744
	global_load_dwordx4 v[52:55], v[212:213], off offset:760
	global_load_dwordx4 v[56:59], v[212:213], off offset:868
	global_load_dwordx4 v[60:63], v[212:213], off offset:884
	s_waitcnt vmcnt(0)
	v_mul_f32_e32 v32, 0x41000000, v32
	v_mul_f32_e32 v33, 0x41000000, v33
	v_mul_f32_e32 v34, 0x41000000, v34
	v_mul_f32_e32 v35, 0x41000000, v35
	v_mul_f32_e32 v36, 0x41000000, v36
	v_mul_f32_e32 v37, 0x41000000, v37
	v_mul_f32_e32 v38, 0x41000000, v38
	v_mul_f32_e32 v39, 0x41000000, v39
	v_cndmask_b32_e64 v32, v216, v32, s[26:27]
	v_cndmask_b32_e64 v33, v216, v33, s[36:37]
	v_cndmask_b32_e64 v34, v216, v34, s[10:11]
	v_cndmask_b32_e64 v35, v216, v35, s[0:1]
	v_cndmask_b32_e64 v36, v216, v36, s[6:7]
	v_cndmask_b32_e64 v37, v216, v37, s[8:9]
	v_cndmask_b32_e64 v38, v216, v38, s[16:17]
	v_cndmask_b32_e64 v39, v216, v39, s[20:21]
	v_mul_f32_e32 v40, 0x41000000, v40
	v_mul_f32_e32 v41, 0x41000000, v41
	v_mul_f32_e32 v42, 0x41000000, v42
	v_mul_f32_e32 v43, 0x41000000, v43
	v_mul_f32_e32 v44, 0x41000000, v44
	v_mul_f32_e32 v45, 0x41000000, v45
	v_mul_f32_e32 v46, 0x41000000, v46
	v_mul_f32_e32 v47, 0x41000000, v47
	v_cndmask_b32_e64 v40, v216, v40, s[26:27]
	v_cndmask_b32_e64 v41, v216, v41, s[36:37]
	v_cndmask_b32_e64 v42, v216, v42, s[10:11]
	v_cndmask_b32_e64 v43, v216, v43, s[0:1]
	v_cndmask_b32_e64 v44, v216, v44, s[6:7]
	v_cndmask_b32_e64 v45, v216, v45, s[8:9]
	v_cndmask_b32_e64 v46, v216, v46, s[16:17]
	v_cndmask_b32_e64 v47, v216, v47, s[20:21]
	v_mul_f32_e32 v48, 0x41000000, v48
	v_mul_f32_e32 v49, 0x41000000, v49
	v_mul_f32_e32 v50, 0x41000000, v50
	v_mul_f32_e32 v51, 0x41000000, v51
	v_mul_f32_e32 v52, 0x41000000, v52
	v_mul_f32_e32 v53, 0x41000000, v53
	v_mul_f32_e32 v54, 0x41000000, v54
	v_mul_f32_e32 v55, 0x41000000, v55
	v_cndmask_b32_e64 v48, v216, v48, s[26:27]
	v_cndmask_b32_e64 v49, v216, v49, s[36:37]
	v_cndmask_b32_e64 v50, v216, v50, s[10:11]
	v_cndmask_b32_e64 v51, v216, v51, s[0:1]
	v_cndmask_b32_e64 v52, v216, v52, s[6:7]
	v_cndmask_b32_e64 v53, v216, v53, s[8:9]
	v_cndmask_b32_e64 v54, v216, v54, s[16:17]
	v_cndmask_b32_e64 v55, v216, v55, s[20:21]
	v_mul_f32_e32 v56, 0x41000000, v56
	v_mul_f32_e32 v57, 0x41000000, v57
	v_mul_f32_e32 v58, 0x41000000, v58
	v_mul_f32_e32 v59, 0x41000000, v59
	v_mul_f32_e32 v60, 0x41000000, v60
	v_mul_f32_e32 v61, 0x41000000, v61
	v_mul_f32_e32 v62, 0x41000000, v62
	v_mul_f32_e32 v63, 0x41000000, v63
	v_cndmask_b32_e64 v56, v216, v56, s[26:27]
	v_cndmask_b32_e64 v57, v216, v57, s[36:37]
	v_cndmask_b32_e64 v58, v216, v58, s[10:11]
	v_cndmask_b32_e64 v59, v216, v59, s[0:1]
	v_cndmask_b32_e64 v60, v216, v60, s[6:7]
	v_cndmask_b32_e64 v61, v216, v61, s[8:9]
	v_cndmask_b32_e64 v62, v216, v62, s[16:17]
	v_cndmask_b32_e64 v63, v216, v63, s[20:21]
	v_readlane_b32 s0, v136, 0
	v_readlane_b32 s1, v136, 1
	v_readlane_b32 s6, v136, 2
	v_readlane_b32 s7, v136, 3
	v_readlane_b32 s8, v136, 4
	v_readlane_b32 s9, v136, 5
	v_mfma_f32_16x16x32_bf16 v[0:3], v[138:141], v[128:131], v[0:3]
	v_mfma_f32_16x16x32_bf16 v[0:3], v[142:145], v[132:135], v[0:3]
	global_load_dwordx4 v[138:141], v209, s[22:23] offset:2048
	global_load_dwordx4 v[142:145], v209, s[22:23] offset:2112
	s_add_u32 s22, s22, 0x3800
	s_addc_u32 s23, s23, 0
	v_mfma_f32_16x16x32_bf16 v[4:7], v[146:149], v[128:131], v[4:7]
	v_mfma_f32_16x16x32_bf16 v[4:7], v[150:153], v[132:135], v[4:7]
	global_load_dwordx4 v[146:149], v209, s[22:23] offset:2048
	global_load_dwordx4 v[150:153], v209, s[22:23] offset:2112
	s_add_u32 s22, s22, 0x34800
	s_addc_u32 s23, s23, 0
	v_mfma_f32_16x16x32_bf16 v[8:11], v[154:157], v[128:131], v[8:11]
	v_mfma_f32_16x16x32_bf16 v[8:11], v[158:161], v[132:135], v[8:11]
	global_load_dwordx4 v[154:157], v209, s[22:23] offset:2048
	global_load_dwordx4 v[158:161], v209, s[22:23] offset:2112
	s_add_u32 s22, s22, 0x3800
	s_addc_u32 s23, s23, 0
	v_mfma_f32_16x16x32_bf16 v[12:15], v[162:165], v[128:131], v[12:15]
	v_mfma_f32_16x16x32_bf16 v[12:15], v[166:169], v[132:135], v[12:15]
	global_load_dwordx4 v[162:165], v209, s[22:23] offset:2048
	global_load_dwordx4 v[166:169], v209, s[22:23] offset:2112
	s_add_u32 s22, s22, 0x34800
	s_addc_u32 s23, s23, 0
	v_mfma_f32_16x16x32_bf16 v[16:19], v[170:173], v[128:131], v[16:19]
	v_mfma_f32_16x16x32_bf16 v[16:19], v[174:177], v[132:135], v[16:19]
	global_load_dwordx4 v[170:173], v209, s[22:23] offset:2048
	global_load_dwordx4 v[174:177], v209, s[22:23] offset:2112
	s_add_u32 s22, s22, 0x3800
	s_addc_u32 s23, s23, 0
	v_mfma_f32_16x16x32_bf16 v[20:23], v[178:181], v[128:131], v[20:23]
	v_mfma_f32_16x16x32_bf16 v[20:23], v[182:185], v[132:135], v[20:23]
	global_load_dwordx4 v[178:181], v209, s[22:23] offset:2048
	global_load_dwordx4 v[182:185], v209, s[22:23] offset:2112
	s_add_u32 s22, s22, 0x34800
	s_addc_u32 s23, s23, 0
	s_waitcnt vmcnt(11)
	v_mfma_f32_16x16x32_bf16 v[24:27], v[138:141], v[128:131], v[24:27]
	s_waitcnt vmcnt(10)
	v_mfma_f32_16x16x32_bf16 v[24:27], v[142:145], v[132:135], v[24:27]
	global_load_dwordx4 v[138:141], v209, s[22:23] offset:2048
	global_load_dwordx4 v[142:145], v209, s[22:23] offset:2112
	s_add_u32 s22, s22, 0x3800
	s_addc_u32 s23, s23, 0
	s_waitcnt vmcnt(11)
	v_mfma_f32_16x16x32_bf16 v[28:31], v[146:149], v[128:131], v[28:31]
	s_waitcnt vmcnt(10)
	v_mfma_f32_16x16x32_bf16 v[28:31], v[150:153], v[132:135], v[28:31]
	global_load_dwordx4 v[146:149], v209, s[22:23] offset:2048
	global_load_dwordx4 v[150:153], v209, s[22:23] offset:2112
	s_add_u32 s22, s22, 0x34800
	s_addc_u32 s23, s23, 0
	s_waitcnt vmcnt(11)
	v_mfma_f32_16x16x32_bf16 v[32:35], v[154:157], v[128:131], v[32:35]
	s_waitcnt vmcnt(10)
	v_mfma_f32_16x16x32_bf16 v[32:35], v[158:161], v[132:135], v[32:35]
	global_load_dwordx4 v[154:157], v209, s[22:23] offset:2048
	global_load_dwordx4 v[158:161], v209, s[22:23] offset:2112
	s_add_u32 s22, s22, 0x3800
	s_addc_u32 s23, s23, 0
	s_waitcnt vmcnt(11)
	v_mfma_f32_16x16x32_bf16 v[36:39], v[162:165], v[128:131], v[36:39]
	s_waitcnt vmcnt(10)
	v_mfma_f32_16x16x32_bf16 v[36:39], v[166:169], v[132:135], v[36:39]
	global_load_dwordx4 v[162:165], v209, s[22:23] offset:2048
	global_load_dwordx4 v[166:169], v209, s[22:23] offset:2112
	s_waitcnt vmcnt(11)
	v_mfma_f32_16x16x32_bf16 v[40:43], v[170:173], v[128:131], v[40:43]
	s_waitcnt vmcnt(10)
	v_mfma_f32_16x16x32_bf16 v[40:43], v[174:177], v[132:135], v[40:43]
	s_barrier
	ds_read_b128 v[170:173], v211 offset:0
	ds_read_b128 v[174:177], v211 offset:1024
	s_waitcnt vmcnt(9)
	v_mfma_f32_16x16x32_bf16 v[44:47], v[178:181], v[128:131], v[44:47]
	s_waitcnt vmcnt(8)
	v_mfma_f32_16x16x32_bf16 v[44:47], v[182:185], v[132:135], v[44:47]
	ds_read_b128 v[178:181], v211 offset:2048
	ds_read_b128 v[182:185], v211 offset:3072
	s_waitcnt vmcnt(7)
	v_mfma_f32_16x16x32_bf16 v[48:51], v[138:141], v[128:131], v[48:51]
	s_waitcnt vmcnt(6)
	v_mfma_f32_16x16x32_bf16 v[48:51], v[142:145], v[132:135], v[48:51]
	ds_read_b128 v[138:141], v211 offset:4096
	ds_read_b128 v[142:145], v211 offset:5120
	s_waitcnt vmcnt(5)
	v_mfma_f32_16x16x32_bf16 v[52:55], v[146:149], v[128:131], v[52:55]
	s_waitcnt vmcnt(4)
	v_mfma_f32_16x16x32_bf16 v[52:55], v[150:153], v[132:135], v[52:55]
	ds_read_b128 v[146:149], v211 offset:6144
	ds_read_b128 v[150:153], v211 offset:7168
	s_waitcnt vmcnt(3)
	v_mfma_f32_16x16x32_bf16 v[56:59], v[154:157], v[128:131], v[56:59]
	s_waitcnt vmcnt(2)
	v_mfma_f32_16x16x32_bf16 v[56:59], v[158:161], v[132:135], v[56:59]
	ds_read_b128 v[154:157], v211 offset:8192
	ds_read_b128 v[158:161], v211 offset:9216
	s_waitcnt vmcnt(1)
	v_mfma_f32_16x16x32_bf16 v[60:63], v[162:165], v[128:131], v[60:63]
	s_waitcnt vmcnt(0)
	v_mfma_f32_16x16x32_bf16 v[60:63], v[166:169], v[132:135], v[60:63]
	ds_read_b128 v[162:165], v211 offset:10240
	ds_read_b128 v[166:169], v211 offset:11264
	s_waitcnt lgkmcnt(11)
	v_mfma_f32_16x16x32_bf16 v[64:67], v[170:173], v[128:131], 0
	s_waitcnt lgkmcnt(10)
	v_mfma_f32_16x16x32_bf16 v[64:67], v[174:177], v[132:135], v[64:67]
	ds_read_b128 v[170:173], v211 offset:12288
	ds_read_b128 v[174:177], v211 offset:13312
	s_waitcnt lgkmcnt(11)
	v_mfma_f32_16x16x32_bf16 v[68:71], v[178:181], v[128:131], 0
	s_waitcnt lgkmcnt(10)
	v_mfma_f32_16x16x32_bf16 v[68:71], v[182:185], v[132:135], v[68:71]
	ds_read_b128 v[178:181], v211 offset:14336
	ds_read_b128 v[182:185], v211 offset:15360
	s_waitcnt lgkmcnt(11)
	v_mfma_f32_16x16x32_bf16 v[72:75], v[138:141], v[128:131], 0
	s_waitcnt lgkmcnt(10)
	v_mfma_f32_16x16x32_bf16 v[72:75], v[142:145], v[132:135], v[72:75]
	ds_read_b128 v[138:141], v211 offset:16384
	ds_read_b128 v[142:145], v211 offset:17408
	s_waitcnt lgkmcnt(11)
	v_mfma_f32_16x16x32_bf16 v[76:79], v[146:149], v[128:131], 0
	s_waitcnt lgkmcnt(10)
	v_mfma_f32_16x16x32_bf16 v[76:79], v[150:153], v[132:135], v[76:79]
	ds_read_b128 v[146:149], v211 offset:18432
	ds_read_b128 v[150:153], v211 offset:19456
	s_waitcnt lgkmcnt(11)
	v_mfma_f32_16x16x32_bf16 v[80:83], v[154:157], v[128:131], 0
	s_waitcnt lgkmcnt(10)
	v_mfma_f32_16x16x32_bf16 v[80:83], v[158:161], v[132:135], v[80:83]
	ds_read_b128 v[154:157], v211 offset:20480
	ds_read_b128 v[158:161], v211 offset:21504
	s_waitcnt lgkmcnt(11)
	v_mfma_f32_16x16x32_bf16 v[84:87], v[162:165], v[128:131], 0
	s_waitcnt lgkmcnt(10)
	v_mfma_f32_16x16x32_bf16 v[84:87], v[166:169], v[132:135], v[84:87]
	ds_read_b128 v[162:165], v211 offset:22528
	ds_read_b128 v[166:169], v211 offset:23552
	s_waitcnt lgkmcnt(11)
	v_mfma_f32_16x16x32_bf16 v[88:91], v[170:173], v[128:131], 0
	s_waitcnt lgkmcnt(10)
	v_mfma_f32_16x16x32_bf16 v[88:91], v[174:177], v[132:135], v[88:91]
	ds_read_b128 v[170:173], v211 offset:24576
	ds_read_b128 v[174:177], v211 offset:25600
	s_waitcnt lgkmcnt(11)
	v_mfma_f32_16x16x32_bf16 v[92:95], v[178:181], v[128:131], 0
	s_waitcnt lgkmcnt(10)
	v_mfma_f32_16x16x32_bf16 v[92:95], v[182:185], v[132:135], v[92:95]
	ds_read_b128 v[178:181], v211 offset:26624
	ds_read_b128 v[182:185], v211 offset:27648
	s_waitcnt lgkmcnt(11)
	v_mfma_f32_16x16x32_bf16 v[96:99], v[138:141], v[128:131], 0
	s_waitcnt lgkmcnt(10)
	v_mfma_f32_16x16x32_bf16 v[96:99], v[142:145], v[132:135], v[96:99]
	ds_read_b128 v[138:141], v211 offset:28672
	ds_read_b128 v[142:145], v211 offset:29696
	s_waitcnt lgkmcnt(11)
	v_mfma_f32_16x16x32_bf16 v[100:103], v[146:149], v[128:131], 0
	s_waitcnt lgkmcnt(10)
	v_mfma_f32_16x16x32_bf16 v[100:103], v[150:153], v[132:135], v[100:103]
	ds_read_b128 v[146:149], v211 offset:30720
	ds_read_b128 v[150:153], v211 offset:31744
	s_waitcnt lgkmcnt(11)
	v_mfma_f32_16x16x32_bf16 v[104:107], v[154:157], v[128:131], 0
	s_waitcnt lgkmcnt(10)
	v_mfma_f32_16x16x32_bf16 v[104:107], v[158:161], v[132:135], v[104:107]
	s_waitcnt lgkmcnt(9)
	v_mfma_f32_16x16x32_bf16 v[108:111], v[162:165], v[128:131], 0
	s_waitcnt lgkmcnt(8)
	v_mfma_f32_16x16x32_bf16 v[108:111], v[166:169], v[132:135], v[108:111]
	s_waitcnt lgkmcnt(7)
	v_mfma_f32_16x16x32_bf16 v[112:115], v[170:173], v[128:131], 0
	s_waitcnt lgkmcnt(6)
	v_mfma_f32_16x16x32_bf16 v[112:115], v[174:177], v[132:135], v[112:115]
	s_waitcnt lgkmcnt(5)
	v_mfma_f32_16x16x32_bf16 v[116:119], v[178:181], v[128:131], 0
	s_waitcnt lgkmcnt(4)
	v_mfma_f32_16x16x32_bf16 v[116:119], v[182:185], v[132:135], v[116:119]
	s_waitcnt lgkmcnt(3)
	v_mfma_f32_16x16x32_bf16 v[120:123], v[138:141], v[128:131], 0
	s_waitcnt lgkmcnt(2)
	v_mfma_f32_16x16x32_bf16 v[120:123], v[142:145], v[132:135], v[120:123]
	s_waitcnt lgkmcnt(1)
	v_mfma_f32_16x16x32_bf16 v[124:127], v[146:149], v[128:131], 0
	s_waitcnt lgkmcnt(0)
	v_mfma_f32_16x16x32_bf16 v[124:127], v[150:153], v[132:135], v[124:127]
	v_lshlrev_b32_e32 v210, 13, v206
	v_lshl_add_u32 v210, v207, 4, v210
	s_lshl_b32 s10, s8, 8
	s_lshl_b32 s11, s6, 6
	s_add_i32 s10, s10, s11
	s_lshl_b32 s11, s10, 13
	s_lshl_b32 s38, s7, 7
	s_add_i32 s11, s11, s38
	s_lshl_b32 s38, s9, 1
	s_add_i32 s11, s11, s38
	s_add_u32 s11, s11, 0x9a00000
	s_add_u32 s16, s4, s11
	s_addc_u32 s17, s5, 0
	s_add_u32 s18, s16, 0x20000
	s_addc_u32 s19, s17, 0
	s_add_u32 s20, s18, 0x20000
	s_addc_u32 s21, s19, 0
	s_add_u32 s22, s20, 0x20000
	s_addc_u32 s23, s21, 0
	s_lshl_b32 s11, s10, 9
	s_add_u32 s11, s11, 0xa200000
	s_add_u32 s24, s4, s11
	s_addc_u32 s25, s5, 0
	s_add_u32 s26, s24, 0x2000
	s_addc_u32 s27, s25, 0
	s_add_u32 s36, s26, 0x2000
	s_addc_u32 s37, s27, 0
	s_lshl_b32 s10, s8, 12
	s_lshl_b32 s11, s1, 6
	s_add_i32 s10, s10, s11
	s_lshl_b32 s11, s0, 4
	s_add_i32 s10, s10, s11
	s_addk_i32 s10, 0x400
	s_mul_i32 s10, s10, 0x600
	s_lshl_b32 s11, s6, 7
	s_add_i32 s10, s10, s11
	s_add_u32 s38, s10, 0xdf00400
	s_add_u32 s0, s36, 0x2000
	s_addc_u32 s1, s37, 0
	global_load_dwordx4 v[138:141], v210, s[16:17] offset:0
	global_load_dwordx4 v[142:145], v210, s[18:19] offset:0
	global_load_dwordx4 v[146:149], v210, s[20:21] offset:0
	global_load_dwordx4 v[150:153], v210, s[22:23] offset:0
	global_load_dwordx4 v[154:157], v210, s[16:17] offset:128
	global_load_dwordx4 v[158:161], v210, s[18:19] offset:128
	global_load_dwordx4 v[162:165], v210, s[20:21] offset:128
	global_load_dwordx4 v[166:169], v210, s[22:23] offset:128
	global_load_dwordx4 v[170:173], v210, s[16:17] offset:256
	global_load_dwordx4 v[174:177], v210, s[18:19] offset:256
	s_nop 7
	v_max3_f32 v214, v0, v1, v2
	v_max3_f32 v214, v214, v3, v4
	v_max3_f32 v214, v214, v5, v6
	v_max3_f32 v214, v214, v7, v8
	v_max3_f32 v214, v214, v9, v10
	v_max3_f32 v214, v214, v11, v12
	v_max3_f32 v214, v214, v13, v14
	v_max3_f32 v214, v214, v15, v16
	v_max3_f32 v214, v214, v17, v18
	v_max3_f32 v214, v214, v19, v20
	v_max3_f32 v214, v214, v21, v22
	v_max3_f32 v214, v214, v23, v24
	v_max3_f32 v214, v214, v25, v26
	v_max3_f32 v214, v214, v27, v28
	v_max3_f32 v214, v214, v29, v30
	v_max3_f32 v214, v214, v31, v32
	v_max3_f32 v214, v214, v33, v34
	v_max3_f32 v214, v214, v35, v36
	v_max3_f32 v214, v214, v37, v38
	v_max3_f32 v214, v214, v39, v40
	v_max3_f32 v214, v214, v41, v42
	v_max3_f32 v214, v214, v43, v44
	v_max3_f32 v214, v214, v45, v46
	v_max3_f32 v214, v214, v47, v48
	v_max3_f32 v214, v214, v49, v50
	v_max3_f32 v214, v214, v51, v52
	v_max3_f32 v214, v214, v53, v54
	v_max3_f32 v214, v214, v55, v56
	v_max3_f32 v214, v214, v57, v58
	v_max3_f32 v214, v214, v59, v60
	v_max3_f32 v214, v214, v61, v62
	v_max3_f32 v214, v214, v63, v64
	v_max3_f32 v214, v214, v65, v66
	v_max3_f32 v214, v214, v67, v68
	v_max3_f32 v214, v214, v69, v70
	v_max3_f32 v214, v214, v71, v72
	v_max3_f32 v214, v214, v73, v74
	v_max3_f32 v214, v214, v75, v76
	v_max3_f32 v214, v214, v77, v78
	v_max3_f32 v214, v214, v79, v80
	v_max3_f32 v214, v214, v81, v82
	v_max3_f32 v214, v214, v83, v84
	v_max3_f32 v214, v214, v85, v86
	v_max3_f32 v214, v214, v87, v88
	v_max3_f32 v214, v214, v89, v90
	v_max3_f32 v214, v214, v91, v92
	v_max3_f32 v214, v214, v93, v94
	v_max3_f32 v214, v214, v95, v96
	v_max3_f32 v214, v214, v97, v98
	v_max3_f32 v214, v214, v99, v100
	v_max3_f32 v214, v214, v101, v102
	v_max3_f32 v214, v214, v103, v104
	v_max3_f32 v214, v214, v105, v106
	v_max3_f32 v214, v214, v107, v108
	v_max3_f32 v214, v214, v109, v110
	v_max3_f32 v214, v214, v111, v112
	v_max3_f32 v214, v214, v113, v114
	v_max3_f32 v214, v214, v115, v116
	v_max3_f32 v214, v214, v117, v118
	v_max3_f32 v214, v214, v119, v120
	v_max3_f32 v214, v214, v121, v122
	v_max3_f32 v214, v214, v123, v124
	v_max3_f32 v214, v214, v125, v126
	v_max_f32_e32 v214, v214, v127
	v_xor_b32_e32 v215, 16, v205
	v_lshlrev_b32_e32 v215, 2, v215
	v_xor_b32_e32 v216, 32, v205
	v_lshlrev_b32_e32 v216, 2, v216
	ds_bpermute_b32 v136, v215, v214
	s_waitcnt lgkmcnt(0)
	v_max_f32_e32 v214, v214, v136
	ds_bpermute_b32 v136, v216, v214
	s_waitcnt lgkmcnt(0)
	v_max_f32_e32 v214, v214, v136
	v_mul_f32_e32 v214, 0xbe38aa3b, v214
	s_mov_b32 s10, 0x3e38aa3b
	v_mov_b32_e32 v212, 0
	v_mov_b32_e32 v213, 0
	v_fma_f32 v0, v0, s10, v214
	v_fma_f32 v1, v1, s10, v214
	v_fma_f32 v2, v2, s10, v214
	v_fma_f32 v3, v3, s10, v214
	v_fma_f32 v4, v4, s10, v214
	v_fma_f32 v5, v5, s10, v214
	v_fma_f32 v6, v6, s10, v214
	v_fma_f32 v7, v7, s10, v214
	v_exp_f32_e32 v0, v0
	v_exp_f32_e32 v1, v1
	v_exp_f32_e32 v2, v2
	v_exp_f32_e32 v3, v3
	v_exp_f32_e32 v4, v4
	v_exp_f32_e32 v5, v5
	v_exp_f32_e32 v6, v6
	v_exp_f32_e32 v7, v7
	s_nop 0
	v_add_f32_e32 v212, v212, v0
	v_add_f32_e32 v213, v213, v1
	v_add_f32_e32 v212, v212, v2
	v_add_f32_e32 v213, v213, v3
	v_add_f32_e32 v212, v212, v4
	v_add_f32_e32 v213, v213, v5
	v_add_f32_e32 v212, v212, v6
	v_add_f32_e32 v213, v213, v7
	v_cvt_pk_bf16_f32 v0, v0, v1
	v_cvt_pk_bf16_f32 v1, v2, v3
	v_cvt_pk_bf16_f32 v2, v4, v5
	v_cvt_pk_bf16_f32 v3, v6, v7
	v_fma_f32 v8, v8, s10, v214
	v_fma_f32 v9, v9, s10, v214
	v_fma_f32 v10, v10, s10, v214
	v_fma_f32 v11, v11, s10, v214
	v_fma_f32 v12, v12, s10, v214
	v_fma_f32 v13, v13, s10, v214
	v_fma_f32 v14, v14, s10, v214
	v_fma_f32 v15, v15, s10, v214
	v_exp_f32_e32 v8, v8
	v_exp_f32_e32 v9, v9
	v_exp_f32_e32 v10, v10
	v_exp_f32_e32 v11, v11
	v_exp_f32_e32 v12, v12
	v_exp_f32_e32 v13, v13
	v_exp_f32_e32 v14, v14
	v_exp_f32_e32 v15, v15
	s_nop 0
	v_add_f32_e32 v212, v212, v8
	v_add_f32_e32 v213, v213, v9
	v_add_f32_e32 v212, v212, v10
	v_add_f32_e32 v213, v213, v11
	v_add_f32_e32 v212, v212, v12
	v_add_f32_e32 v213, v213, v13
	v_add_f32_e32 v212, v212, v14
	v_add_f32_e32 v213, v213, v15
	v_cvt_pk_bf16_f32 v8, v8, v9
	v_cvt_pk_bf16_f32 v9, v10, v11
	v_cvt_pk_bf16_f32 v10, v12, v13
	v_cvt_pk_bf16_f32 v11, v14, v15
	v_fma_f32 v16, v16, s10, v214
	v_fma_f32 v17, v17, s10, v214
	v_fma_f32 v18, v18, s10, v214
	v_fma_f32 v19, v19, s10, v214
	v_fma_f32 v20, v20, s10, v214
	v_fma_f32 v21, v21, s10, v214
	v_fma_f32 v22, v22, s10, v214
	v_fma_f32 v23, v23, s10, v214
	v_exp_f32_e32 v16, v16
	v_exp_f32_e32 v17, v17
	v_exp_f32_e32 v18, v18
	v_exp_f32_e32 v19, v19
	v_exp_f32_e32 v20, v20
	v_exp_f32_e32 v21, v21
	v_exp_f32_e32 v22, v22
	v_exp_f32_e32 v23, v23
	s_nop 0
	v_add_f32_e32 v212, v212, v16
	v_add_f32_e32 v213, v213, v17
	v_add_f32_e32 v212, v212, v18
	v_add_f32_e32 v213, v213, v19
	v_add_f32_e32 v212, v212, v20
	v_add_f32_e32 v213, v213, v21
	v_add_f32_e32 v212, v212, v22
	v_add_f32_e32 v213, v213, v23
	v_cvt_pk_bf16_f32 v16, v16, v17
	v_cvt_pk_bf16_f32 v17, v18, v19
	v_cvt_pk_bf16_f32 v18, v20, v21
	v_cvt_pk_bf16_f32 v19, v22, v23
	v_fma_f32 v24, v24, s10, v214
	v_fma_f32 v25, v25, s10, v214
	v_fma_f32 v26, v26, s10, v214
	v_fma_f32 v27, v27, s10, v214
	v_fma_f32 v28, v28, s10, v214
	v_fma_f32 v29, v29, s10, v214
	v_fma_f32 v30, v30, s10, v214
	v_fma_f32 v31, v31, s10, v214
	v_exp_f32_e32 v24, v24
	v_exp_f32_e32 v25, v25
	v_exp_f32_e32 v26, v26
	v_exp_f32_e32 v27, v27
	v_exp_f32_e32 v28, v28
	v_exp_f32_e32 v29, v29
	v_exp_f32_e32 v30, v30
	v_exp_f32_e32 v31, v31
	s_nop 0
	v_add_f32_e32 v212, v212, v24
	v_add_f32_e32 v213, v213, v25
	v_add_f32_e32 v212, v212, v26
	v_add_f32_e32 v213, v213, v27
	v_add_f32_e32 v212, v212, v28
	v_add_f32_e32 v213, v213, v29
	v_add_f32_e32 v212, v212, v30
	v_add_f32_e32 v213, v213, v31
	v_cvt_pk_bf16_f32 v24, v24, v25
	v_cvt_pk_bf16_f32 v25, v26, v27
	v_cvt_pk_bf16_f32 v26, v28, v29
	v_cvt_pk_bf16_f32 v27, v30, v31
	v_fma_f32 v32, v32, s10, v214
	v_fma_f32 v33, v33, s10, v214
	v_fma_f32 v34, v34, s10, v214
	v_fma_f32 v35, v35, s10, v214
	v_fma_f32 v36, v36, s10, v214
	v_fma_f32 v37, v37, s10, v214
	v_fma_f32 v38, v38, s10, v214
	v_fma_f32 v39, v39, s10, v214
	v_exp_f32_e32 v32, v32
	v_exp_f32_e32 v33, v33
	v_exp_f32_e32 v34, v34
	v_exp_f32_e32 v35, v35
	v_exp_f32_e32 v36, v36
	v_exp_f32_e32 v37, v37
	v_exp_f32_e32 v38, v38
	v_exp_f32_e32 v39, v39
	s_nop 0
	v_add_f32_e32 v212, v212, v32
	v_add_f32_e32 v213, v213, v33
	v_add_f32_e32 v212, v212, v34
	v_add_f32_e32 v213, v213, v35
	v_add_f32_e32 v212, v212, v36
	v_add_f32_e32 v213, v213, v37
	v_add_f32_e32 v212, v212, v38
	v_add_f32_e32 v213, v213, v39
	v_cvt_pk_bf16_f32 v32, v32, v33
	v_cvt_pk_bf16_f32 v33, v34, v35
	v_cvt_pk_bf16_f32 v34, v36, v37
	v_cvt_pk_bf16_f32 v35, v38, v39
	v_fma_f32 v40, v40, s10, v214
	v_fma_f32 v41, v41, s10, v214
	v_fma_f32 v42, v42, s10, v214
	v_fma_f32 v43, v43, s10, v214
	v_fma_f32 v44, v44, s10, v214
	v_fma_f32 v45, v45, s10, v214
	v_fma_f32 v46, v46, s10, v214
	v_fma_f32 v47, v47, s10, v214
	v_exp_f32_e32 v40, v40
	v_exp_f32_e32 v41, v41
	v_exp_f32_e32 v42, v42
	v_exp_f32_e32 v43, v43
	v_exp_f32_e32 v44, v44
	v_exp_f32_e32 v45, v45
	v_exp_f32_e32 v46, v46
	v_exp_f32_e32 v47, v47
	s_nop 0
	v_add_f32_e32 v212, v212, v40
	v_add_f32_e32 v213, v213, v41
	v_add_f32_e32 v212, v212, v42
	v_add_f32_e32 v213, v213, v43
	v_add_f32_e32 v212, v212, v44
	v_add_f32_e32 v213, v213, v45
	v_add_f32_e32 v212, v212, v46
	v_add_f32_e32 v213, v213, v47
	v_cvt_pk_bf16_f32 v40, v40, v41
	v_cvt_pk_bf16_f32 v41, v42, v43
	v_cvt_pk_bf16_f32 v42, v44, v45
	v_cvt_pk_bf16_f32 v43, v46, v47
	v_fma_f32 v48, v48, s10, v214
	v_fma_f32 v49, v49, s10, v214
	v_fma_f32 v50, v50, s10, v214
	v_fma_f32 v51, v51, s10, v214
	v_fma_f32 v52, v52, s10, v214
	v_fma_f32 v53, v53, s10, v214
	v_fma_f32 v54, v54, s10, v214
	v_fma_f32 v55, v55, s10, v214
	v_exp_f32_e32 v48, v48
	v_exp_f32_e32 v49, v49
	v_exp_f32_e32 v50, v50
	v_exp_f32_e32 v51, v51
	v_exp_f32_e32 v52, v52
	v_exp_f32_e32 v53, v53
	v_exp_f32_e32 v54, v54
	v_exp_f32_e32 v55, v55
	s_nop 0
	v_add_f32_e32 v212, v212, v48
	v_add_f32_e32 v213, v213, v49
	v_add_f32_e32 v212, v212, v50
	v_add_f32_e32 v213, v213, v51
	v_add_f32_e32 v212, v212, v52
	v_add_f32_e32 v213, v213, v53
	v_add_f32_e32 v212, v212, v54
	v_add_f32_e32 v213, v213, v55
	v_cvt_pk_bf16_f32 v48, v48, v49
	v_cvt_pk_bf16_f32 v49, v50, v51
	v_cvt_pk_bf16_f32 v50, v52, v53
	v_cvt_pk_bf16_f32 v51, v54, v55
	v_fma_f32 v56, v56, s10, v214
	v_fma_f32 v57, v57, s10, v214
	v_fma_f32 v58, v58, s10, v214
	v_fma_f32 v59, v59, s10, v214
	v_fma_f32 v60, v60, s10, v214
	v_fma_f32 v61, v61, s10, v214
	v_fma_f32 v62, v62, s10, v214
	v_fma_f32 v63, v63, s10, v214
	v_exp_f32_e32 v56, v56
	v_exp_f32_e32 v57, v57
	v_exp_f32_e32 v58, v58
	v_exp_f32_e32 v59, v59
	v_exp_f32_e32 v60, v60
	v_exp_f32_e32 v61, v61
	v_exp_f32_e32 v62, v62
	v_exp_f32_e32 v63, v63
	s_nop 0
	v_add_f32_e32 v212, v212, v56
	v_add_f32_e32 v213, v213, v57
	v_add_f32_e32 v212, v212, v58
	v_add_f32_e32 v213, v213, v59
	v_add_f32_e32 v212, v212, v60
	v_add_f32_e32 v213, v213, v61
	v_add_f32_e32 v212, v212, v62
	v_add_f32_e32 v213, v213, v63
	v_cvt_pk_bf16_f32 v56, v56, v57
	v_cvt_pk_bf16_f32 v57, v58, v59
	v_cvt_pk_bf16_f32 v58, v60, v61
	v_cvt_pk_bf16_f32 v59, v62, v63
	v_fma_f32 v64, v64, s10, v214
	v_fma_f32 v65, v65, s10, v214
	v_fma_f32 v66, v66, s10, v214
	v_fma_f32 v67, v67, s10, v214
	v_fma_f32 v68, v68, s10, v214
	v_fma_f32 v69, v69, s10, v214
	v_fma_f32 v70, v70, s10, v214
	v_fma_f32 v71, v71, s10, v214
	v_exp_f32_e32 v64, v64
	v_exp_f32_e32 v65, v65
	v_exp_f32_e32 v66, v66
	v_exp_f32_e32 v67, v67
	v_exp_f32_e32 v68, v68
	v_exp_f32_e32 v69, v69
	v_exp_f32_e32 v70, v70
	v_exp_f32_e32 v71, v71
	s_nop 0
	v_add_f32_e32 v212, v212, v64
	v_add_f32_e32 v213, v213, v65
	v_add_f32_e32 v212, v212, v66
	v_add_f32_e32 v213, v213, v67
	v_add_f32_e32 v212, v212, v68
	v_add_f32_e32 v213, v213, v69
	v_add_f32_e32 v212, v212, v70
	v_add_f32_e32 v213, v213, v71
	v_cvt_pk_bf16_f32 v64, v64, v65
	v_cvt_pk_bf16_f32 v65, v66, v67
	v_cvt_pk_bf16_f32 v66, v68, v69
	v_cvt_pk_bf16_f32 v67, v70, v71
	v_fma_f32 v72, v72, s10, v214
	v_fma_f32 v73, v73, s10, v214
	v_fma_f32 v74, v74, s10, v214
	v_fma_f32 v75, v75, s10, v214
	v_fma_f32 v76, v76, s10, v214
	v_fma_f32 v77, v77, s10, v214
	v_fma_f32 v78, v78, s10, v214
	v_fma_f32 v79, v79, s10, v214
	v_exp_f32_e32 v72, v72
	v_exp_f32_e32 v73, v73
	v_exp_f32_e32 v74, v74
	v_exp_f32_e32 v75, v75
	v_exp_f32_e32 v76, v76
	v_exp_f32_e32 v77, v77
	v_exp_f32_e32 v78, v78
	v_exp_f32_e32 v79, v79
	s_nop 0
	v_add_f32_e32 v212, v212, v72
	v_add_f32_e32 v213, v213, v73
	v_add_f32_e32 v212, v212, v74
	v_add_f32_e32 v213, v213, v75
	v_add_f32_e32 v212, v212, v76
	v_add_f32_e32 v213, v213, v77
	v_add_f32_e32 v212, v212, v78
	v_add_f32_e32 v213, v213, v79
	v_cvt_pk_bf16_f32 v72, v72, v73
	v_cvt_pk_bf16_f32 v73, v74, v75
	v_cvt_pk_bf16_f32 v74, v76, v77
	v_cvt_pk_bf16_f32 v75, v78, v79
	v_fma_f32 v80, v80, s10, v214
	v_fma_f32 v81, v81, s10, v214
	v_fma_f32 v82, v82, s10, v214
	v_fma_f32 v83, v83, s10, v214
	v_fma_f32 v84, v84, s10, v214
	v_fma_f32 v85, v85, s10, v214
	v_fma_f32 v86, v86, s10, v214
	v_fma_f32 v87, v87, s10, v214
	v_exp_f32_e32 v80, v80
	v_exp_f32_e32 v81, v81
	v_exp_f32_e32 v82, v82
	v_exp_f32_e32 v83, v83
	v_exp_f32_e32 v84, v84
	v_exp_f32_e32 v85, v85
	v_exp_f32_e32 v86, v86
	v_exp_f32_e32 v87, v87
	s_nop 0
	v_add_f32_e32 v212, v212, v80
	v_add_f32_e32 v213, v213, v81
	v_add_f32_e32 v212, v212, v82
	v_add_f32_e32 v213, v213, v83
	v_add_f32_e32 v212, v212, v84
	v_add_f32_e32 v213, v213, v85
	v_add_f32_e32 v212, v212, v86
	v_add_f32_e32 v213, v213, v87
	v_cvt_pk_bf16_f32 v80, v80, v81
	v_cvt_pk_bf16_f32 v81, v82, v83
	v_cvt_pk_bf16_f32 v82, v84, v85
	v_cvt_pk_bf16_f32 v83, v86, v87
	v_fma_f32 v88, v88, s10, v214
	v_fma_f32 v89, v89, s10, v214
	v_fma_f32 v90, v90, s10, v214
	v_fma_f32 v91, v91, s10, v214
	v_fma_f32 v92, v92, s10, v214
	v_fma_f32 v93, v93, s10, v214
	v_fma_f32 v94, v94, s10, v214
	v_fma_f32 v95, v95, s10, v214
	v_exp_f32_e32 v88, v88
	v_exp_f32_e32 v89, v89
	v_exp_f32_e32 v90, v90
	v_exp_f32_e32 v91, v91
	v_exp_f32_e32 v92, v92
	v_exp_f32_e32 v93, v93
	v_exp_f32_e32 v94, v94
	v_exp_f32_e32 v95, v95
	s_nop 0
	v_add_f32_e32 v212, v212, v88
	v_add_f32_e32 v213, v213, v89
	v_add_f32_e32 v212, v212, v90
	v_add_f32_e32 v213, v213, v91
	v_add_f32_e32 v212, v212, v92
	v_add_f32_e32 v213, v213, v93
	v_add_f32_e32 v212, v212, v94
	v_add_f32_e32 v213, v213, v95
	v_cvt_pk_bf16_f32 v88, v88, v89
	v_cvt_pk_bf16_f32 v89, v90, v91
	v_cvt_pk_bf16_f32 v90, v92, v93
	v_cvt_pk_bf16_f32 v91, v94, v95
	v_fma_f32 v96, v96, s10, v214
	v_fma_f32 v97, v97, s10, v214
	v_fma_f32 v98, v98, s10, v214
	v_fma_f32 v99, v99, s10, v214
	v_fma_f32 v100, v100, s10, v214
	v_fma_f32 v101, v101, s10, v214
	v_fma_f32 v102, v102, s10, v214
	v_fma_f32 v103, v103, s10, v214
	v_exp_f32_e32 v96, v96
	v_exp_f32_e32 v97, v97
	v_exp_f32_e32 v98, v98
	v_exp_f32_e32 v99, v99
	v_exp_f32_e32 v100, v100
	v_exp_f32_e32 v101, v101
	v_exp_f32_e32 v102, v102
	v_exp_f32_e32 v103, v103
	s_nop 0
	v_add_f32_e32 v212, v212, v96
	v_add_f32_e32 v213, v213, v97
	v_add_f32_e32 v212, v212, v98
	v_add_f32_e32 v213, v213, v99
	v_add_f32_e32 v212, v212, v100
	v_add_f32_e32 v213, v213, v101
	v_add_f32_e32 v212, v212, v102
	v_add_f32_e32 v213, v213, v103
	v_cvt_pk_bf16_f32 v96, v96, v97
	v_cvt_pk_bf16_f32 v97, v98, v99
	v_cvt_pk_bf16_f32 v98, v100, v101
	v_cvt_pk_bf16_f32 v99, v102, v103
	v_fma_f32 v104, v104, s10, v214
	v_fma_f32 v105, v105, s10, v214
	v_fma_f32 v106, v106, s10, v214
	v_fma_f32 v107, v107, s10, v214
	v_fma_f32 v108, v108, s10, v214
	v_fma_f32 v109, v109, s10, v214
	v_fma_f32 v110, v110, s10, v214
	v_fma_f32 v111, v111, s10, v214
	v_exp_f32_e32 v104, v104
	v_exp_f32_e32 v105, v105
	v_exp_f32_e32 v106, v106
	v_exp_f32_e32 v107, v107
	v_exp_f32_e32 v108, v108
	v_exp_f32_e32 v109, v109
	v_exp_f32_e32 v110, v110
	v_exp_f32_e32 v111, v111
	s_nop 0
	v_add_f32_e32 v212, v212, v104
	v_add_f32_e32 v213, v213, v105
	v_add_f32_e32 v212, v212, v106
	v_add_f32_e32 v213, v213, v107
	v_add_f32_e32 v212, v212, v108
	v_add_f32_e32 v213, v213, v109
	v_add_f32_e32 v212, v212, v110
	v_add_f32_e32 v213, v213, v111
	v_cvt_pk_bf16_f32 v104, v104, v105
	v_cvt_pk_bf16_f32 v105, v106, v107
	v_cvt_pk_bf16_f32 v106, v108, v109
	v_cvt_pk_bf16_f32 v107, v110, v111
	v_fma_f32 v112, v112, s10, v214
	v_fma_f32 v113, v113, s10, v214
	v_fma_f32 v114, v114, s10, v214
	v_fma_f32 v115, v115, s10, v214
	v_fma_f32 v116, v116, s10, v214
	v_fma_f32 v117, v117, s10, v214
	v_fma_f32 v118, v118, s10, v214
	v_fma_f32 v119, v119, s10, v214
	v_exp_f32_e32 v112, v112
	v_exp_f32_e32 v113, v113
	v_exp_f32_e32 v114, v114
	v_exp_f32_e32 v115, v115
	v_exp_f32_e32 v116, v116
	v_exp_f32_e32 v117, v117
	v_exp_f32_e32 v118, v118
	v_exp_f32_e32 v119, v119
	s_nop 0
	v_add_f32_e32 v212, v212, v112
	v_add_f32_e32 v213, v213, v113
	v_add_f32_e32 v212, v212, v114
	v_add_f32_e32 v213, v213, v115
	v_add_f32_e32 v212, v212, v116
	v_add_f32_e32 v213, v213, v117
	v_add_f32_e32 v212, v212, v118
	v_add_f32_e32 v213, v213, v119
	v_cvt_pk_bf16_f32 v112, v112, v113
	v_cvt_pk_bf16_f32 v113, v114, v115
	v_cvt_pk_bf16_f32 v114, v116, v117
	v_cvt_pk_bf16_f32 v115, v118, v119
	v_fma_f32 v120, v120, s10, v214
	v_fma_f32 v121, v121, s10, v214
	v_fma_f32 v122, v122, s10, v214
	v_fma_f32 v123, v123, s10, v214
	v_fma_f32 v124, v124, s10, v214
	v_fma_f32 v125, v125, s10, v214
	v_fma_f32 v126, v126, s10, v214
	v_fma_f32 v127, v127, s10, v214
	v_exp_f32_e32 v120, v120
	v_exp_f32_e32 v121, v121
	v_exp_f32_e32 v122, v122
	v_exp_f32_e32 v123, v123
	v_exp_f32_e32 v124, v124
	v_exp_f32_e32 v125, v125
	v_exp_f32_e32 v126, v126
	v_exp_f32_e32 v127, v127
	s_nop 0
	v_add_f32_e32 v212, v212, v120
	v_add_f32_e32 v213, v213, v121
	v_add_f32_e32 v212, v212, v122
	v_add_f32_e32 v213, v213, v123
	v_add_f32_e32 v212, v212, v124
	v_add_f32_e32 v213, v213, v125
	v_add_f32_e32 v212, v212, v126
	v_add_f32_e32 v213, v213, v127
	v_cvt_pk_bf16_f32 v120, v120, v121
	v_cvt_pk_bf16_f32 v121, v122, v123
	v_cvt_pk_bf16_f32 v122, v124, v125
	v_cvt_pk_bf16_f32 v123, v126, v127
	v_add_f32_e32 v212, v212, v213
	global_load_dwordx4 v[4:7], v210, s[20:21] offset:256
	global_load_dwordx4 v[12:15], v210, s[22:23] offset:256
	global_load_dwordx4 v[20:23], v210, s[16:17] offset:384
	global_load_dwordx4 v[28:31], v210, s[18:19] offset:384
	global_load_dwordx4 v[36:39], v210, s[20:21] offset:384
	global_load_dwordx4 v[44:47], v210, s[22:23] offset:384
	global_load_dwordx4 v[52:55], v210, s[16:17] offset:512
	global_load_dwordx4 v[60:63], v210, s[18:19] offset:512
	global_load_dwordx4 v[68:71], v210, s[20:21] offset:512
	global_load_dwordx4 v[76:79], v210, s[22:23] offset:512
	global_load_dwordx4 v[84:87], v210, s[16:17] offset:640
	global_load_dwordx4 v[92:95], v210, s[18:19] offset:640
	global_load_dwordx4 v[100:103], v210, s[20:21] offset:640
	global_load_dwordx4 v[108:111], v210, s[22:23] offset:640
	global_load_dwordx4 v[116:119], v210, s[16:17] offset:768
	global_load_dwordx4 v[124:127], v210, s[18:19] offset:768
	s_waitcnt vmcnt(25)
	v_mfma_f32_16x16x32_bf16 v[128:131], v[138:141], v[0:3], 0
	global_load_dwordx4 v[138:141], v210, s[20:21] offset:768
	s_waitcnt vmcnt(25)
	v_mfma_f32_16x16x32_bf16 v[132:135], v[142:145], v[0:3], 0
	global_load_dwordx4 v[142:145], v210, s[22:23] offset:768
	s_waitcnt vmcnt(25)
	v_mfma_f32_16x16x32_bf16 v[178:181], v[146:149], v[0:3], 0
	global_load_dwordx4 v[146:149], v210, s[16:17] offset:896
	s_waitcnt vmcnt(25)
	v_mfma_f32_16x16x32_bf16 v[182:185], v[150:153], v[0:3], 0
	global_load_dwordx4 v[150:153], v210, s[18:19] offset:896
	s_waitcnt vmcnt(25)
	v_mfma_f32_16x16x32_bf16 v[128:131], v[154:157], v[8:11], v[128:131]
	global_load_dwordx4 v[154:157], v210, s[20:21] offset:896
	s_waitcnt vmcnt(25)
	v_mfma_f32_16x16x32_bf16 v[132:135], v[158:161], v[8:11], v[132:135]
	global_load_dwordx4 v[158:161], v210, s[22:23] offset:896
	s_waitcnt vmcnt(25)
	v_mfma_f32_16x16x32_bf16 v[178:181], v[162:165], v[8:11], v[178:181]
	s_waitcnt vmcnt(24)
	v_mfma_f32_16x16x32_bf16 v[182:185], v[166:169], v[8:11], v[182:185]
	s_waitcnt vmcnt(23)
	v_mfma_f32_16x16x32_bf16 v[128:131], v[170:173], v[16:19], v[128:131]
	s_waitcnt vmcnt(22)
	v_mfma_f32_16x16x32_bf16 v[132:135], v[174:177], v[16:19], v[132:135]
	s_waitcnt vmcnt(21)
	v_mfma_f32_16x16x32_bf16 v[178:181], v[4:7], v[16:19], v[178:181]
	s_waitcnt vmcnt(20)
	v_mfma_f32_16x16x32_bf16 v[182:185], v[12:15], v[16:19], v[182:185]
	s_waitcnt vmcnt(19)
	v_mfma_f32_16x16x32_bf16 v[128:131], v[20:23], v[24:27], v[128:131]
	s_waitcnt vmcnt(18)
	v_mfma_f32_16x16x32_bf16 v[132:135], v[28:31], v[24:27], v[132:135]
	s_waitcnt vmcnt(17)
	v_mfma_f32_16x16x32_bf16 v[178:181], v[36:39], v[24:27], v[178:181]
	s_waitcnt vmcnt(16)
	v_mfma_f32_16x16x32_bf16 v[182:185], v[44:47], v[24:27], v[182:185]
	s_waitcnt vmcnt(15)
	v_mfma_f32_16x16x32_bf16 v[128:131], v[52:55], v[32:35], v[128:131]
	s_waitcnt vmcnt(14)
	v_mfma_f32_16x16x32_bf16 v[132:135], v[60:63], v[32:35], v[132:135]
	s_waitcnt vmcnt(13)
	v_mfma_f32_16x16x32_bf16 v[178:181], v[68:71], v[32:35], v[178:181]
	s_waitcnt vmcnt(12)
	v_mfma_f32_16x16x32_bf16 v[182:185], v[76:79], v[32:35], v[182:185]
	s_waitcnt vmcnt(11)
	v_mfma_f32_16x16x32_bf16 v[128:131], v[84:87], v[40:43], v[128:131]
	s_waitcnt vmcnt(10)
	v_mfma_f32_16x16x32_bf16 v[132:135], v[92:95], v[40:43], v[132:135]
	s_waitcnt vmcnt(9)
	v_mfma_f32_16x16x32_bf16 v[178:181], v[100:103], v[40:43], v[178:181]
	s_waitcnt vmcnt(8)
	v_mfma_f32_16x16x32_bf16 v[182:185], v[108:111], v[40:43], v[182:185]
	s_waitcnt vmcnt(7)
	v_mfma_f32_16x16x32_bf16 v[128:131], v[116:119], v[48:51], v[128:131]
	s_waitcnt vmcnt(6)
	v_mfma_f32_16x16x32_bf16 v[132:135], v[124:127], v[48:51], v[132:135]
	s_waitcnt vmcnt(5)
	v_mfma_f32_16x16x32_bf16 v[178:181], v[138:141], v[48:51], v[178:181]
	s_waitcnt vmcnt(4)
	v_mfma_f32_16x16x32_bf16 v[182:185], v[142:145], v[48:51], v[182:185]
	s_waitcnt vmcnt(3)
	v_mfma_f32_16x16x32_bf16 v[128:131], v[146:149], v[56:59], v[128:131]
	ds_read_b128 v[162:165], v211 offset:32768
	s_waitcnt vmcnt(2)
	v_mfma_f32_16x16x32_bf16 v[132:135], v[150:153], v[56:59], v[132:135]
	ds_read_b128 v[166:169], v211 offset:33792
	s_waitcnt vmcnt(1)
	v_mfma_f32_16x16x32_bf16 v[178:181], v[154:157], v[56:59], v[178:181]
	ds_read_b128 v[170:173], v211 offset:34816
	s_waitcnt vmcnt(0)
	v_mfma_f32_16x16x32_bf16 v[182:185], v[158:161], v[56:59], v[182:185]
	ds_read_b128 v[174:177], v211 offset:35840
	s_waitcnt lgkmcnt(3)
	v_mfma_f32_16x16x32_bf16 v[128:131], v[162:165], v[64:67], v[128:131]
	ds_read_b128 v[4:7], v211 offset:36864
	s_waitcnt lgkmcnt(3)
	v_mfma_f32_16x16x32_bf16 v[132:135], v[166:169], v[64:67], v[132:135]
	ds_read_b128 v[12:15], v211 offset:37888
	s_waitcnt lgkmcnt(3)
	v_mfma_f32_16x16x32_bf16 v[178:181], v[170:173], v[64:67], v[178:181]
	ds_read_b128 v[20:23], v211 offset:38912
	s_waitcnt lgkmcnt(3)
	v_mfma_f32_16x16x32_bf16 v[182:185], v[174:177], v[64:67], v[182:185]
	ds_read_b128 v[28:31], v211 offset:39936
	s_waitcnt lgkmcnt(3)
	v_mfma_f32_16x16x32_bf16 v[128:131], v[4:7], v[72:75], v[128:131]
	ds_read_b128 v[36:39], v211 offset:40960
	s_waitcnt lgkmcnt(3)
	v_mfma_f32_16x16x32_bf16 v[132:135], v[12:15], v[72:75], v[132:135]
	ds_read_b128 v[44:47], v211 offset:41984
	s_waitcnt lgkmcnt(3)
	v_mfma_f32_16x16x32_bf16 v[178:181], v[20:23], v[72:75], v[178:181]
	ds_read_b128 v[52:55], v211 offset:43008
	s_waitcnt lgkmcnt(3)
	v_mfma_f32_16x16x32_bf16 v[182:185], v[28:31], v[72:75], v[182:185]
	ds_read_b128 v[60:63], v211 offset:44032
	s_waitcnt lgkmcnt(3)
	v_mfma_f32_16x16x32_bf16 v[128:131], v[36:39], v[80:83], v[128:131]
	ds_read_b128 v[68:71], v211 offset:45056
	s_waitcnt lgkmcnt(3)
	v_mfma_f32_16x16x32_bf16 v[132:135], v[44:47], v[80:83], v[132:135]
	ds_read_b128 v[76:79], v211 offset:46080
	s_waitcnt lgkmcnt(3)
	v_mfma_f32_16x16x32_bf16 v[178:181], v[52:55], v[80:83], v[178:181]
	ds_read_b128 v[84:87], v211 offset:47104
	s_waitcnt lgkmcnt(3)
	v_mfma_f32_16x16x32_bf16 v[182:185], v[60:63], v[80:83], v[182:185]
	ds_read_b128 v[92:95], v211 offset:48128
	s_waitcnt lgkmcnt(3)
	v_mfma_f32_16x16x32_bf16 v[128:131], v[68:71], v[88:91], v[128:131]
	ds_read_b128 v[100:103], v211 offset:49152
	s_waitcnt lgkmcnt(3)
	v_mfma_f32_16x16x32_bf16 v[132:135], v[76:79], v[88:91], v[132:135]
	ds_read_b128 v[108:111], v211 offset:50176
	s_waitcnt lgkmcnt(3)
	v_mfma_f32_16x16x32_bf16 v[178:181], v[84:87], v[88:91], v[178:181]
	ds_read_b128 v[116:119], v211 offset:51200
	s_waitcnt lgkmcnt(3)
	v_mfma_f32_16x16x32_bf16 v[182:185], v[92:95], v[88:91], v[182:185]
	ds_read_b128 v[124:127], v211 offset:52224
	s_waitcnt lgkmcnt(3)
	v_mfma_f32_16x16x32_bf16 v[128:131], v[100:103], v[96:99], v[128:131]
	ds_read_b128 v[138:141], v211 offset:53248
	s_waitcnt lgkmcnt(3)
	v_mfma_f32_16x16x32_bf16 v[132:135], v[108:111], v[96:99], v[132:135]
	ds_read_b128 v[142:145], v211 offset:54272
	s_waitcnt lgkmcnt(3)
	v_mfma_f32_16x16x32_bf16 v[178:181], v[116:119], v[96:99], v[178:181]
	ds_read_b128 v[146:149], v211 offset:55296
	s_waitcnt lgkmcnt(3)
	v_mfma_f32_16x16x32_bf16 v[182:185], v[124:127], v[96:99], v[182:185]
	ds_read_b128 v[150:153], v211 offset:56320
	s_waitcnt lgkmcnt(3)
	v_mfma_f32_16x16x32_bf16 v[128:131], v[138:141], v[104:107], v[128:131]
	ds_read_b128 v[154:157], v211 offset:57344
	s_waitcnt lgkmcnt(3)
	v_mfma_f32_16x16x32_bf16 v[132:135], v[142:145], v[104:107], v[132:135]
	ds_read_b128 v[158:161], v211 offset:58368
	s_waitcnt lgkmcnt(3)
	v_mfma_f32_16x16x32_bf16 v[178:181], v[146:149], v[104:107], v[178:181]
	ds_read_b128 v[162:165], v211 offset:59392
	s_waitcnt lgkmcnt(3)
	v_mfma_f32_16x16x32_bf16 v[182:185], v[150:153], v[104:107], v[182:185]
	ds_read_b128 v[166:169], v211 offset:60416
	s_waitcnt lgkmcnt(3)
	v_mfma_f32_16x16x32_bf16 v[128:131], v[154:157], v[112:115], v[128:131]
	ds_read_b128 v[170:173], v211 offset:61440
	s_waitcnt lgkmcnt(3)
	v_mfma_f32_16x16x32_bf16 v[132:135], v[158:161], v[112:115], v[132:135]
	ds_read_b128 v[174:177], v211 offset:62464
	s_waitcnt lgkmcnt(3)
	v_mfma_f32_16x16x32_bf16 v[178:181], v[162:165], v[112:115], v[178:181]
	ds_read_b128 v[4:7], v211 offset:63488
	s_waitcnt lgkmcnt(3)
	v_mfma_f32_16x16x32_bf16 v[182:185], v[166:169], v[112:115], v[182:185]
	ds_read_b128 v[12:15], v211 offset:64512
	s_waitcnt lgkmcnt(3)
	v_mfma_f32_16x16x32_bf16 v[128:131], v[170:173], v[120:123], v[128:131]
	s_waitcnt lgkmcnt(2)
	v_mfma_f32_16x16x32_bf16 v[132:135], v[174:177], v[120:123], v[132:135]
	s_waitcnt lgkmcnt(1)
	v_mfma_f32_16x16x32_bf16 v[178:181], v[4:7], v[120:123], v[178:181]
	s_waitcnt lgkmcnt(0)
	v_mfma_f32_16x16x32_bf16 v[182:185], v[12:15], v[120:123], v[182:185]
	ds_bpermute_b32 v136, v215, v212
	s_waitcnt lgkmcnt(0)
	v_add_f32_e32 v212, v212, v136
	ds_bpermute_b32 v136, v216, v212
	s_waitcnt lgkmcnt(0)
	v_add_f32_e32 v212, v212, v136
	v_rcp_f32_e32 v213, v212
	s_nop 0
	v_fma_f32 v136, -v212, v213, 1.0
	v_fma_f32 v213, v136, v213, v213
	v_mul_u32_u24_e32 v208, 0x600, v206
	v_lshl_add_u32 v208, v207, 3, v208
	s_add_u32 s10, s4, s38
	s_addc_u32 s11, s5, 0
	s_nop 2
	v_mul_f32_e32 v128, v128, v213
	v_mul_f32_e32 v129, v129, v213
	v_mul_f32_e32 v130, v130, v213
	v_mul_f32_e32 v131, v131, v213
	v_cvt_pk_bf16_f32 v128, v128, v129
	v_cvt_pk_bf16_f32 v129, v130, v131
	global_store_dwordx2 v208, v[128:129], s[10:11] offset:0
	v_mul_f32_e32 v132, v132, v213
	v_mul_f32_e32 v133, v133, v213
	v_mul_f32_e32 v134, v134, v213
	v_mul_f32_e32 v135, v135, v213
	v_cvt_pk_bf16_f32 v132, v132, v133
	v_cvt_pk_bf16_f32 v133, v134, v135
	global_store_dwordx2 v208, v[132:133], s[10:11] offset:32
	v_mul_f32_e32 v178, v178, v213
	v_mul_f32_e32 v179, v179, v213
	v_mul_f32_e32 v180, v180, v213
	v_mul_f32_e32 v181, v181, v213
	v_cvt_pk_bf16_f32 v178, v178, v179
	v_cvt_pk_bf16_f32 v179, v180, v181
	global_store_dwordx2 v208, v[178:179], s[10:11] offset:64
	v_mul_f32_e32 v182, v182, v213
	v_mul_f32_e32 v183, v183, v213
	v_mul_f32_e32 v184, v184, v213
	v_mul_f32_e32 v185, v185, v213
	v_cvt_pk_bf16_f32 v182, v182, v183
	v_cvt_pk_bf16_f32 v183, v184, v185
	global_store_dwordx2 v208, v[182:183], s[10:11] offset:96
